# attention loop restructured: matrix segment and vector segment separated, the two wave halves staggered by one segment (one barrier per tile per wave), K DMA one tile further ahead
# speedup vs baseline: 1.0107x; 1.0070x over previous
.Lattn_skipq:
	v_lshl_add_u64 v[2:3], s[42:43], 0, v[160:161]
	v_mov_b32_e32 v169, s43
	v_mad_u64_u32 v[0:1], s[42:43], v2, s47, v[0:1]
	v_mad_i32_i24 v1, v3, s47, v1
	v_lshl_add_u64 v[0:1], v[0:1], 0, s[30:31]
	v_mov_b32_e32 v165, v193
	v_lshl_add_u64 v[170:171], v[0:1], 0, v[164:165]
	v_add_u32_e32 v2, s2, v160
	v_mov_b64_e32 v[0:1], s[10:11]
	v_mad_i64_i32 v[0:1], s[42:43], v2, s73, v[0:1]
	s_lshl_b64 s[40:41], s[40:41], 12
	v_lshl_add_u64 v[0:1], v[0:1], 0, s[40:41]
	s_mul_i32 s2, s38, 0x88000
	v_lshl_add_u64 v[172:173], v[0:1], 0, v[164:165]
	s_lshl_b32 s31, s38, 1
	s_not_b64 s[38:39], s[16:17]
	v_and_b32_e32 v34, 64, v240
	v_xor_b32_e32 v33, 32, v240
	v_add_u32_e32 v34, 64, v34
	v_cmp_lt_i32_e32 vcc, v33, v34
	s_nop 1
	v_cndmask_b32_e32 v33, v240, v33, vcc
	v_lshlrev_b32_e32 v165, 2, v33
	s_mov_b32 s42, s31
	v_subrev_u32_e32 v170, s6, v170
	v_subrev_u32_e32 v172, s10, v172
	s_cmp_lg_u32 s35, 0
	s_cbranch_scc0 .Lattn_pro_np
	s_add_i32 s2, s42, 2
	s_and_b32 s2, s2, 31
	s_mul_i32 s2, s2, 0x44000
	s_add_i32 m0, s5, 32768
	s_add_u32 s40, s26, s2
	s_addc_u32 s41, s27, 0
	global_load_lds_dwordx4 v170, s[40:41]
	s_add_i32 m0, s5, 40960
	s_add_u32 s40, s40, 0x80
	s_addc_u32 s41, s41, 0
	global_load_lds_dwordx4 v170, s[40:41]
	s_add_i32 s2, s42, 1
	s_and_b32 s2, s2, 31
	s_lshl_b32 s2, s2, 7
	s_add_i32 m0, s5, 81920
	s_add_u32 s44, s10, s2
	s_addc_u32 s45, s11, 0
	global_load_lds_dwordx4 v172, s[44:45]
	s_add_i32 m0, s5, 90112
	s_add_u32 s44, s44, 0x204000
	s_addc_u32 s45, s45, 0
	global_load_lds_dwordx4 v172, s[44:45]
	s_add_i32 s2, s42, 3
	s_and_b32 s2, s2, 31
	s_mul_i32 s2, s2, 0x44000
	s_add_i32 m0, s5, 49152
	s_add_u32 s40, s26, s2
	s_addc_u32 s41, s27, 0
	global_load_lds_dwordx4 v170, s[40:41]
	s_add_i32 m0, s5, 57344
	s_add_u32 s40, s40, 0x80
	s_addc_u32 s41, s41, 0
	global_load_lds_dwordx4 v170, s[40:41]
	v_mov_b32_e32 v128, v144
	v_mov_b32_e32 v129, v145
	v_mov_b32_e32 v130, v146
	v_mov_b32_e32 v131, v147
	v_mov_b32_e32 v132, v148
	v_mov_b32_e32 v133, v149
	v_mov_b32_e32 v134, v150
	v_mov_b32_e32 v135, v151
	v_mov_b32_e32 v0, 0
	v_mov_b32_e32 v1, 0
	v_mov_b32_e32 v2, 0
	v_mov_b32_e32 v3, 0
	v_mov_b32_e32 v4, 0
	v_mov_b32_e32 v5, 0
	v_mov_b32_e32 v6, 0
	v_mov_b32_e32 v7, 0
	v_mov_b32_e32 v8, 0
	v_mov_b32_e32 v9, 0
	v_mov_b32_e32 v10, 0
	v_mov_b32_e32 v11, 0
	v_mov_b32_e32 v12, 0
	v_mov_b32_e32 v13, 0
	v_mov_b32_e32 v14, 0
	v_mov_b32_e32 v15, 0
	v_mov_b32_e32 v16, 0
	v_mov_b32_e32 v17, 0
	v_mov_b32_e32 v18, 0
	v_mov_b32_e32 v19, 0
	v_mov_b32_e32 v20, 0
	v_mov_b32_e32 v21, 0
	v_mov_b32_e32 v22, 0
	v_mov_b32_e32 v23, 0
	v_mov_b32_e32 v24, 0
	v_mov_b32_e32 v25, 0
	v_mov_b32_e32 v26, 0
	v_mov_b32_e32 v27, 0
	v_mov_b32_e32 v28, 0
	v_mov_b32_e32 v29, 0
	v_mov_b32_e32 v30, 0
	v_mov_b32_e32 v31, 0
	v_mov_b32_e32 v32, 0
	v_mov_b32_e32 v33, 0
	v_mov_b32_e32 v34, 0
	v_mov_b32_e32 v35, 0
	v_mov_b32_e32 v36, 0
	v_mov_b32_e32 v37, 0
	v_mov_b32_e32 v38, 0
	v_mov_b32_e32 v39, 0
	v_mov_b32_e32 v40, 0
	v_mov_b32_e32 v41, 0
	v_mov_b32_e32 v42, 0
	v_mov_b32_e32 v43, 0
	v_mov_b32_e32 v44, 0
	v_mov_b32_e32 v45, 0
	v_mov_b32_e32 v46, 0
	v_mov_b32_e32 v47, 0
	v_mov_b32_e32 v48, 0
	v_mov_b32_e32 v49, 0
	v_mov_b32_e32 v50, 0
	v_mov_b32_e32 v51, 0
	v_mov_b32_e32 v52, 0
	v_mov_b32_e32 v53, 0
	v_mov_b32_e32 v54, 0
	v_mov_b32_e32 v55, 0
	v_mov_b32_e32 v56, 0
	v_mov_b32_e32 v57, 0
	v_mov_b32_e32 v58, 0
	v_mov_b32_e32 v59, 0
	v_mov_b32_e32 v60, 0
	v_mov_b32_e32 v61, 0
	v_mov_b32_e32 v62, 0
	v_mov_b32_e32 v63, 0
	v_mov_b32_e32 v167, 0
	v_mov_b32_e32 v175, 0
	v_mov_b32_e32 v174, 1.0
	s_waitcnt vmcnt(6)
	s_branch .Lattn_pro_join
.Lattn_pro_np:
	s_add_i32 s2, s42, 0
	s_and_b32 s2, s2, 31
	s_mul_i32 s2, s2, 0x44000
	s_add_i32 m0, s5, 0
	s_add_u32 s40, s26, s2
	s_addc_u32 s41, s27, 0
	global_load_lds_dwordx4 v170, s[40:41]
	s_add_i32 m0, s5, 8192
	s_add_u32 s40, s40, 0x80
	s_addc_u32 s41, s41, 0
	global_load_lds_dwordx4 v170, s[40:41]
	s_add_i32 s2, s42, 1
	s_and_b32 s2, s2, 31
	s_mul_i32 s2, s2, 0x44000
	s_add_i32 m0, s5, 16384
	s_add_u32 s40, s26, s2
	s_addc_u32 s41, s27, 0
	global_load_lds_dwordx4 v170, s[40:41]
	s_add_i32 m0, s5, 24576
	s_add_u32 s40, s40, 0x80
	s_addc_u32 s41, s41, 0
	global_load_lds_dwordx4 v170, s[40:41]
	s_add_i32 s2, s42, 0
	s_and_b32 s2, s2, 31
	s_lshl_b32 s2, s2, 7
	s_add_i32 m0, s5, 65536
	s_add_u32 s44, s10, s2
	s_addc_u32 s45, s11, 0
	global_load_lds_dwordx4 v172, s[44:45]
	s_add_i32 m0, s5, 73728
	s_add_u32 s44, s44, 0x204000
	s_addc_u32 s45, s45, 0
	global_load_lds_dwordx4 v172, s[44:45]
	s_add_i32 s2, s42, 2
	s_and_b32 s2, s2, 31
	s_mul_i32 s2, s2, 0x44000
	s_add_i32 m0, s5, 32768
	s_add_u32 s40, s26, s2
	s_addc_u32 s41, s27, 0
	global_load_lds_dwordx4 v170, s[40:41]
	s_add_i32 m0, s5, 40960
	s_add_u32 s40, s40, 0x80
	s_addc_u32 s41, s41, 0
	global_load_lds_dwordx4 v170, s[40:41]
	s_add_i32 s2, s42, 1
	s_and_b32 s2, s2, 31
	s_lshl_b32 s2, s2, 7
	s_add_i32 m0, s5, 81920
	s_add_u32 s44, s10, s2
	s_addc_u32 s45, s11, 0
	global_load_lds_dwordx4 v172, s[44:45]
	s_add_i32 m0, s5, 90112
	s_add_u32 s44, s44, 0x204000
	s_addc_u32 s45, s45, 0
	global_load_lds_dwordx4 v172, s[44:45]
	s_add_i32 s2, s42, 3
	s_and_b32 s2, s2, 31
	s_mul_i32 s2, s2, 0x44000
	s_add_i32 m0, s5, 49152
	s_add_u32 s40, s26, s2
	s_addc_u32 s41, s27, 0
	global_load_lds_dwordx4 v170, s[40:41]
	s_add_i32 m0, s5, 57344
	s_add_u32 s40, s40, 0x80
	s_addc_u32 s41, s41, 0
	global_load_lds_dwordx4 v170, s[40:41]
	v_mov_b32_e32 v0, 0
	v_mov_b32_e32 v1, 0
	v_mov_b32_e32 v2, 0
	v_mov_b32_e32 v3, 0
	v_mov_b32_e32 v4, 0
	v_mov_b32_e32 v5, 0
	v_mov_b32_e32 v6, 0
	v_mov_b32_e32 v7, 0
	v_mov_b32_e32 v8, 0
	v_mov_b32_e32 v9, 0
	v_mov_b32_e32 v10, 0
	v_mov_b32_e32 v11, 0
	v_mov_b32_e32 v12, 0
	v_mov_b32_e32 v13, 0
	v_mov_b32_e32 v14, 0
	v_mov_b32_e32 v15, 0
	v_mov_b32_e32 v16, 0
	v_mov_b32_e32 v17, 0
	v_mov_b32_e32 v18, 0
	v_mov_b32_e32 v19, 0
	v_mov_b32_e32 v20, 0
	v_mov_b32_e32 v21, 0
	v_mov_b32_e32 v22, 0
	v_mov_b32_e32 v23, 0
	v_mov_b32_e32 v24, 0
	v_mov_b32_e32 v25, 0
	v_mov_b32_e32 v26, 0
	v_mov_b32_e32 v27, 0
	v_mov_b32_e32 v28, 0
	v_mov_b32_e32 v29, 0
	v_mov_b32_e32 v30, 0
	v_mov_b32_e32 v31, 0
	v_mov_b32_e32 v32, 0
	v_mov_b32_e32 v33, 0
	v_mov_b32_e32 v34, 0
	v_mov_b32_e32 v35, 0
	v_mov_b32_e32 v36, 0
	v_mov_b32_e32 v37, 0
	v_mov_b32_e32 v38, 0
	v_mov_b32_e32 v39, 0
	v_mov_b32_e32 v40, 0
	v_mov_b32_e32 v41, 0
	v_mov_b32_e32 v42, 0
	v_mov_b32_e32 v43, 0
	v_mov_b32_e32 v44, 0
	v_mov_b32_e32 v45, 0
	v_mov_b32_e32 v46, 0
	v_mov_b32_e32 v47, 0
	v_mov_b32_e32 v48, 0
	v_mov_b32_e32 v49, 0
	v_mov_b32_e32 v50, 0
	v_mov_b32_e32 v51, 0
	v_mov_b32_e32 v52, 0
	v_mov_b32_e32 v53, 0
	v_mov_b32_e32 v54, 0
	v_mov_b32_e32 v55, 0
	v_mov_b32_e32 v56, 0
	v_mov_b32_e32 v57, 0
	v_mov_b32_e32 v58, 0
	v_mov_b32_e32 v59, 0
	v_mov_b32_e32 v60, 0
	v_mov_b32_e32 v61, 0
	v_mov_b32_e32 v62, 0
	v_mov_b32_e32 v63, 0
	v_mov_b32_e32 v167, 0
	v_mov_b32_e32 v175, 0
	v_mov_b32_e32 v174, 1.0
	s_waitcnt vmcnt(10)
.Lattn_pro_join:
	s_barrier
	ds_read_b128 v[96:99], v182 offset:0
	ds_read_b128 v[100:103], v182 offset:4096
	ds_read_b128 v[104:107], v183 offset:0
	ds_read_b128 v[108:111], v183 offset:4096
	ds_read_b128 v[112:115], v184 offset:0
	ds_read_b128 v[116:119], v184 offset:4096
	ds_read_b128 v[120:123], v185 offset:0
	ds_read_b128 v[124:127], v185 offset:4096
	s_waitcnt lgkmcnt(0)
	v_mfma_f32_32x32x16_bf16 v[64:79], v[96:99], v[128:131], 0
	v_mfma_f32_32x32x16_bf16 v[80:95], v[100:103], v[128:131], 0
	v_mfma_f32_32x32x16_bf16 v[64:79], v[104:107], v[132:135], v[64:79]
	v_mfma_f32_32x32x16_bf16 v[80:95], v[108:111], v[132:135], v[80:95]
	v_mfma_f32_32x32x16_bf16 v[64:79], v[112:115], v[136:139], v[64:79]
	v_mfma_f32_32x32x16_bf16 v[80:95], v[116:119], v[136:139], v[80:95]
	v_mfma_f32_32x32x16_bf16 v[64:79], v[120:123], v[140:143], v[64:79]
	v_mfma_f32_32x32x16_bf16 v[80:95], v[124:127], v[140:143], v[80:95]
	s_waitcnt vmcnt(4)
	s_barrier
	ds_read_b128 v[208:211], v182 offset:16384
	ds_read_b128 v[212:215], v182 offset:20480
	ds_read_b128 v[216:219], v183 offset:16384
	ds_read_b128 v[220:223], v183 offset:20480
	ds_read_b128 v[224:227], v184 offset:16384
	ds_read_b128 v[228:231], v184 offset:20480
	s_nop 7
	s_cmp_lg_u32 s14, 0
	s_cbranch_scc1 .Lattn_tb1
	s_barrier
.Lattn_tb1:
	s_waitcnt lgkmcnt(5)
	v_mfma_f32_32x32x16_bf16 v[96:111], v[208:211], v[128:131], 0
	ds_read_b128 v[208:211], v185 offset:16384
	s_waitcnt lgkmcnt(5)
	v_mfma_f32_32x32x16_bf16 v[112:127], v[212:215], v[128:131], 0
	ds_read_b128 v[212:215], v185 offset:20480
	s_waitcnt lgkmcnt(5)
	v_mfma_f32_32x32x16_bf16 v[96:111], v[216:219], v[132:135], v[96:111]
	s_waitcnt lgkmcnt(4)
	v_mfma_f32_32x32x16_bf16 v[112:127], v[220:223], v[132:135], v[112:127]
	s_waitcnt lgkmcnt(3)
	v_mfma_f32_32x32x16_bf16 v[96:111], v[224:227], v[136:139], v[96:111]
	s_waitcnt lgkmcnt(2)
	v_mfma_f32_32x32x16_bf16 v[112:127], v[228:231], v[136:139], v[112:127]
	s_waitcnt lgkmcnt(1)
	v_mfma_f32_32x32x16_bf16 v[96:111], v[208:211], v[140:143], v[96:111]
	s_waitcnt lgkmcnt(0)
	v_mfma_f32_32x32x16_bf16 v[112:127], v[212:215], v[140:143], v[112:127]
	s_cmp_lg_u32 s14, 0
	s_cbranch_scc0 .Lattn_tb2
	s_barrier
.Lattn_tb2:
	ds_read_b128 v[216:219], v187 offset:0
	ds_read_b128 v[220:223], v187 offset:4096
	ds_read_b128 v[224:227], v187 offset:8192
	ds_read_b128 v[228:231], v187 offset:12288
	ds_read_b128 v[208:211], v188 offset:0
	ds_read_b128 v[212:215], v188 offset:4096
	v_max3_f32 v254, v64, v65, v66
	s_add_i32 s2, s42, 4
	v_max3_f32 v255, v80, v81, v82
	s_and_b32 s2, s2, 31
	v_max3_f32 v254, v254, v67, v68
	s_mul_i32 s2, s2, 0x44000
	v_max3_f32 v255, v255, v83, v84
	s_add_i32 m0, s5, 0
	v_max3_f32 v254, v254, v69, v70
	s_add_u32 s40, s26, s2
	v_max3_f32 v255, v255, v85, v86
	s_addc_u32 s41, s27, 0
	v_max3_f32 v254, v254, v71, v72
	global_load_lds_dwordx4 v170, s[40:41]
	v_max3_f32 v255, v255, v87, v88
	s_add_i32 m0, s5, 8192
	v_max3_f32 v254, v254, v73, v74
	s_add_u32 s40, s40, 0x80
	v_max3_f32 v255, v255, v89, v90
	s_addc_u32 s41, s41, 0
	v_max3_f32 v254, v254, v75, v76
	global_load_lds_dwordx4 v170, s[40:41]
	v_max3_f32 v255, v255, v91, v92
	s_add_i32 s2, s42, 2
	v_max3_f32 v254, v254, v77, v78
	s_and_b32 s2, s2, 31
	v_max3_f32 v255, v255, v93, v94
	s_lshl_b32 s2, s2, 7
	v_max3_f32 v254, v254, v79, v95
	s_add_i32 m0, s5, 98304
	v_max_f32_e32 v254, v254, v255
	s_add_u32 s44, s10, s2
	s_addc_u32 s45, s11, 0
	global_load_lds_dwordx4 v172, s[44:45]
	s_add_i32 m0, s5, 106496
	s_add_u32 s44, s44, 0x204000
	s_addc_u32 s45, s45, 0
	global_load_lds_dwordx4 v172, s[44:45]
	v_mov_b32_e32 v180, 0xc2800000
	v_cmp_lt_f32_e32 vcc, 0x4138aa3b, v254
	v_cmp_gt_f32_e64 s[40:41], v180, v254
	s_nop 4
	s_or_b64 vcc, vcc, s[40:41]
	s_nop 0
	s_cbranch_vccnz .Lattn_sp_t0
	v_exp_f32_e32 v64, v64
	v_exp_f32_e32 v65, v65
	v_exp_f32_e32 v66, v66
	v_exp_f32_e32 v67, v67
	v_exp_f32_e32 v68, v68
	v_exp_f32_e32 v69, v69
	v_exp_f32_e32 v70, v70
	v_exp_f32_e32 v71, v71
	v_add_f32_e32 v190, v64, v65
	v_add_f32_e32 v191, v66, v67
	v_add_f32_e32 v190, v190, v68
	v_add_f32_e32 v191, v191, v69
	v_add_f32_e32 v190, v190, v70
	v_add_f32_e32 v191, v191, v71
	v_cvt_pk_bf16_f32 v144, v64, v65
	v_cvt_pk_bf16_f32 v145, v66, v67
	v_cvt_pk_bf16_f32 v146, v68, v69
	v_cvt_pk_bf16_f32 v147, v70, v71
	v_exp_f32_e32 v72, v72
	v_exp_f32_e32 v73, v73
	v_exp_f32_e32 v74, v74
	v_exp_f32_e32 v75, v75
	v_exp_f32_e32 v76, v76
	v_exp_f32_e32 v77, v77
	v_exp_f32_e32 v78, v78
	v_exp_f32_e32 v79, v79
	v_add_f32_e32 v190, v190, v72
	v_add_f32_e32 v191, v191, v73
	v_add_f32_e32 v190, v190, v74
	v_add_f32_e32 v191, v191, v75
	v_add_f32_e32 v190, v190, v76
	v_add_f32_e32 v191, v191, v77
	v_add_f32_e32 v190, v190, v78
	v_add_f32_e32 v191, v191, v79
	v_cvt_pk_bf16_f32 v148, v72, v73
	v_cvt_pk_bf16_f32 v149, v74, v75
	v_cvt_pk_bf16_f32 v150, v76, v77
	v_cvt_pk_bf16_f32 v151, v78, v79
	v_exp_f32_e32 v80, v80
	v_exp_f32_e32 v81, v81
	v_exp_f32_e32 v82, v82
	v_exp_f32_e32 v83, v83
	v_exp_f32_e32 v84, v84
	v_exp_f32_e32 v85, v85
	v_exp_f32_e32 v86, v86
	v_exp_f32_e32 v87, v87
	v_add_f32_e32 v190, v190, v80
	v_add_f32_e32 v191, v191, v81
	v_add_f32_e32 v190, v190, v82
	v_add_f32_e32 v191, v191, v83
	v_add_f32_e32 v190, v190, v84
	v_add_f32_e32 v191, v191, v85
	v_add_f32_e32 v190, v190, v86
	v_add_f32_e32 v191, v191, v87
	v_cvt_pk_bf16_f32 v152, v80, v81
	v_cvt_pk_bf16_f32 v153, v82, v83
	v_cvt_pk_bf16_f32 v154, v84, v85
	v_cvt_pk_bf16_f32 v155, v86, v87
	v_exp_f32_e32 v88, v88
	v_exp_f32_e32 v89, v89
	v_exp_f32_e32 v90, v90
	v_exp_f32_e32 v91, v91
	v_exp_f32_e32 v92, v92
	v_exp_f32_e32 v93, v93
	v_exp_f32_e32 v94, v94
	v_exp_f32_e32 v95, v95
	v_add_f32_e32 v190, v190, v88
	v_add_f32_e32 v191, v191, v89
	v_add_f32_e32 v190, v190, v90
	v_add_f32_e32 v191, v191, v91
	v_add_f32_e32 v190, v190, v92
	v_add_f32_e32 v191, v191, v93
	v_add_f32_e32 v190, v190, v94
	v_add_f32_e32 v191, v191, v95
	v_cvt_pk_bf16_f32 v156, v88, v89
	v_cvt_pk_bf16_f32 v157, v90, v91
	v_cvt_pk_bf16_f32 v158, v92, v93
	v_cvt_pk_bf16_f32 v159, v94, v95
	v_add_f32_e32 v190, v190, v191
	v_add_f32_e32 v167, v167, v190
	s_add_i32 s42, s31, 1
	s_movk_i32 s47, 7
.Lattn_loop_f:
	s_cmp_lg_u32 s14, 0
	s_cbranch_scc1 .Lattn_tb3
	s_waitcnt vmcnt(4)
	s_barrier
.Lattn_tb3:
	s_waitcnt lgkmcnt(5)
	v_mfma_f32_32x32x16_bf16 v[48:63], v[216:219], v[144:147], v[48:63]
	ds_read_b128 v[216:219], v188 offset:8192
	s_waitcnt lgkmcnt(5)
	v_mfma_f32_32x32x16_bf16 v[32:47], v[220:223], v[144:147], v[32:47]
	ds_read_b128 v[220:223], v188 offset:12288
	s_waitcnt lgkmcnt(5)
	v_mfma_f32_32x32x16_bf16 v[16:31], v[224:227], v[144:147], v[16:31]
	ds_read_b128 v[224:227], v186 offset:0
	s_waitcnt lgkmcnt(5)
	v_mfma_f32_32x32x16_bf16 v[0:15], v[228:231], v[144:147], v[0:15]
	ds_read_b128 v[228:231], v186 offset:4096
	s_waitcnt lgkmcnt(5)
	v_mfma_f32_32x32x16_bf16 v[48:63], v[208:211], v[148:151], v[48:63]
	ds_read_b128 v[208:211], v186 offset:8192
	s_waitcnt lgkmcnt(5)
	v_mfma_f32_32x32x16_bf16 v[32:47], v[212:215], v[148:151], v[32:47]
	ds_read_b128 v[212:215], v186 offset:12288
	s_waitcnt lgkmcnt(5)
	v_mfma_f32_32x32x16_bf16 v[16:31], v[216:219], v[148:151], v[16:31]
	ds_read_b128 v[216:219], v189 offset:0
	s_waitcnt lgkmcnt(5)
	v_mfma_f32_32x32x16_bf16 v[0:15], v[220:223], v[148:151], v[0:15]
	ds_read_b128 v[220:223], v189 offset:4096
	s_waitcnt lgkmcnt(5)
	v_mfma_f32_32x32x16_bf16 v[48:63], v[224:227], v[152:155], v[48:63]
	ds_read_b128 v[224:227], v189 offset:8192
	s_waitcnt lgkmcnt(5)
	v_mfma_f32_32x32x16_bf16 v[32:47], v[228:231], v[152:155], v[32:47]
	ds_read_b128 v[228:231], v189 offset:12288
	s_waitcnt lgkmcnt(5)
	v_mfma_f32_32x32x16_bf16 v[16:31], v[208:211], v[152:155], v[16:31]
	ds_read_b128 v[208:211], v182 offset:32768
	s_waitcnt lgkmcnt(5)
	v_mfma_f32_32x32x16_bf16 v[0:15], v[212:215], v[152:155], v[0:15]
	ds_read_b128 v[212:215], v182 offset:36864
	s_waitcnt lgkmcnt(5)
	v_mfma_f32_32x32x16_bf16 v[48:63], v[216:219], v[156:159], v[48:63]
	ds_read_b128 v[216:219], v183 offset:32768
	s_waitcnt lgkmcnt(5)
	v_mfma_f32_32x32x16_bf16 v[32:47], v[220:223], v[156:159], v[32:47]
	ds_read_b128 v[220:223], v183 offset:36864
	s_waitcnt lgkmcnt(5)
	v_mfma_f32_32x32x16_bf16 v[16:31], v[224:227], v[156:159], v[16:31]
	ds_read_b128 v[224:227], v184 offset:32768
	s_waitcnt lgkmcnt(5)
	v_mfma_f32_32x32x16_bf16 v[0:15], v[228:231], v[156:159], v[0:15]
	ds_read_b128 v[228:231], v184 offset:36864
	s_waitcnt lgkmcnt(5)
	v_mfma_f32_32x32x16_bf16 v[64:79], v[208:211], v[128:131], 0
	ds_read_b128 v[208:211], v185 offset:32768
	s_waitcnt lgkmcnt(5)
	v_mfma_f32_32x32x16_bf16 v[80:95], v[212:215], v[128:131], 0
	ds_read_b128 v[212:215], v185 offset:36864
	s_waitcnt lgkmcnt(5)
	v_mfma_f32_32x32x16_bf16 v[64:79], v[216:219], v[132:135], v[64:79]
	s_waitcnt lgkmcnt(4)
	v_mfma_f32_32x32x16_bf16 v[80:95], v[220:223], v[132:135], v[80:95]
	s_waitcnt lgkmcnt(3)
	v_mfma_f32_32x32x16_bf16 v[64:79], v[224:227], v[136:139], v[64:79]
	s_waitcnt lgkmcnt(2)
	v_mfma_f32_32x32x16_bf16 v[80:95], v[228:231], v[136:139], v[80:95]
	s_waitcnt lgkmcnt(1)
	v_mfma_f32_32x32x16_bf16 v[64:79], v[208:211], v[140:143], v[64:79]
	s_waitcnt lgkmcnt(0)
	v_mfma_f32_32x32x16_bf16 v[80:95], v[212:215], v[140:143], v[80:95]
	s_cmp_lg_u32 s14, 0
	s_cbranch_scc0 .Lattn_tb4
	s_waitcnt vmcnt(4)
	s_barrier
.Lattn_tb4:
	ds_read_b128 v[216:219], v187 offset:16384
	ds_read_b128 v[220:223], v187 offset:20480
	ds_read_b128 v[224:227], v187 offset:24576
	ds_read_b128 v[228:231], v187 offset:28672
	ds_read_b128 v[208:211], v188 offset:16384
	ds_read_b128 v[212:215], v188 offset:20480
	v_exp_f32_e32 v171, v96
	v_exp_f32_e32 v173, v97
	v_exp_f32_e32 v179, v98
	s_add_i32 s2, s42, 4
	v_exp_f32_e32 v180, v99
	v_exp_f32_e32 v232, v100
	v_exp_f32_e32 v233, v101
	s_and_b32 s2, s2, 31
	v_exp_f32_e32 v234, v102
	v_exp_f32_e32 v235, v103
	v_add_f32_e32 v190, v171, v173
	s_mul_i32 s2, s2, 0x44000
	v_add_f32_e32 v191, v179, v180
	v_add_f32_e32 v190, v190, v232
	v_add_f32_e32 v191, v191, v233
	s_add_i32 m0, s5, 16384
	v_add_f32_e32 v190, v190, v234
	v_add_f32_e32 v191, v191, v235
	v_cvt_pk_bf16_f32 v144, v171, v173
	s_add_u32 s40, s26, s2
	v_cvt_pk_bf16_f32 v145, v179, v180
	v_cvt_pk_bf16_f32 v146, v232, v233
	v_cvt_pk_bf16_f32 v147, v234, v235
	s_addc_u32 s41, s27, 0
	v_exp_f32_e32 v171, v104
	v_exp_f32_e32 v173, v105
	v_exp_f32_e32 v179, v106
	global_load_lds_dwordx4 v170, s[40:41]
	v_exp_f32_e32 v180, v107
	v_exp_f32_e32 v232, v108
	v_exp_f32_e32 v233, v109
	s_add_i32 m0, s5, 24576
	v_exp_f32_e32 v234, v110
	v_exp_f32_e32 v235, v111
	v_add_f32_e32 v190, v190, v171
	s_add_u32 s40, s40, 0x80
	v_add_f32_e32 v191, v191, v173
	v_add_f32_e32 v190, v190, v179
	v_add_f32_e32 v191, v191, v180
	s_addc_u32 s41, s41, 0
	v_add_f32_e32 v190, v190, v232
	v_add_f32_e32 v191, v191, v233
	v_add_f32_e32 v190, v190, v234
	global_load_lds_dwordx4 v170, s[40:41]
	v_add_f32_e32 v191, v191, v235
	v_cvt_pk_bf16_f32 v148, v171, v173
	v_cvt_pk_bf16_f32 v149, v179, v180
	s_add_i32 s2, s42, 2
	v_cvt_pk_bf16_f32 v150, v232, v233
	v_cvt_pk_bf16_f32 v151, v234, v235
	v_exp_f32_e32 v171, v112
	s_and_b32 s2, s2, 31
	v_exp_f32_e32 v173, v113
	v_exp_f32_e32 v179, v114
	v_exp_f32_e32 v180, v115
	s_lshl_b32 s2, s2, 7
	v_exp_f32_e32 v232, v116
	v_exp_f32_e32 v233, v117
	v_exp_f32_e32 v234, v118
	s_add_i32 m0, s5, 114688
	v_exp_f32_e32 v235, v119
	v_add_f32_e32 v190, v190, v171
	v_add_f32_e32 v191, v191, v173
	s_add_u32 s44, s10, s2
	v_add_f32_e32 v190, v190, v179
	v_add_f32_e32 v191, v191, v180
	v_add_f32_e32 v190, v190, v232
	s_addc_u32 s45, s11, 0
	v_add_f32_e32 v191, v191, v233
	v_add_f32_e32 v190, v190, v234
	v_add_f32_e32 v191, v191, v235
	global_load_lds_dwordx4 v172, s[44:45]
	v_cvt_pk_bf16_f32 v152, v171, v173
	v_cvt_pk_bf16_f32 v153, v179, v180
	v_cvt_pk_bf16_f32 v154, v232, v233
	s_add_i32 m0, s5, 122880
	v_cvt_pk_bf16_f32 v155, v234, v235
	v_exp_f32_e32 v171, v120
	v_exp_f32_e32 v173, v121
	s_add_u32 s44, s44, 0x204000
	v_exp_f32_e32 v179, v122
	v_exp_f32_e32 v180, v123
	v_exp_f32_e32 v232, v124
	s_addc_u32 s45, s45, 0
	v_exp_f32_e32 v233, v125
	v_exp_f32_e32 v234, v126
	v_exp_f32_e32 v235, v127
	global_load_lds_dwordx4 v172, s[44:45]
	v_add_f32_e32 v190, v190, v171
	v_add_f32_e32 v191, v191, v173
	v_add_f32_e32 v190, v190, v179
	v_add_f32_e32 v191, v191, v180
	v_add_f32_e32 v190, v190, v232
	v_add_f32_e32 v191, v191, v233
	v_add_f32_e32 v190, v190, v234
	v_add_f32_e32 v191, v191, v235
	v_cvt_pk_bf16_f32 v156, v171, v173
	v_cvt_pk_bf16_f32 v157, v179, v180
	v_cvt_pk_bf16_f32 v158, v232, v233
	v_cvt_pk_bf16_f32 v159, v234, v235
	v_add_f32_e32 v190, v190, v191
	v_cmp_ngt_f32_e32 vcc, 0x71800000, v190
	s_nop 4
	s_cbranch_vccnz .Lattn_redo_L0
	v_add_f32_e32 v167, v167, v190
	s_cmp_lg_u32 s14, 0
	s_cbranch_scc1 .Lattn_tb5
	s_waitcnt vmcnt(4)
	s_barrier
.Lattn_tb5:
	s_waitcnt lgkmcnt(5)
	v_mfma_f32_32x32x16_bf16 v[48:63], v[216:219], v[144:147], v[48:63]
	ds_read_b128 v[216:219], v188 offset:24576
	s_waitcnt lgkmcnt(5)
	v_mfma_f32_32x32x16_bf16 v[32:47], v[220:223], v[144:147], v[32:47]
	ds_read_b128 v[220:223], v188 offset:28672
	s_waitcnt lgkmcnt(5)
	v_mfma_f32_32x32x16_bf16 v[16:31], v[224:227], v[144:147], v[16:31]
	ds_read_b128 v[224:227], v186 offset:16384
	s_waitcnt lgkmcnt(5)
	v_mfma_f32_32x32x16_bf16 v[0:15], v[228:231], v[144:147], v[0:15]
	ds_read_b128 v[228:231], v186 offset:20480
	s_waitcnt lgkmcnt(5)
	v_mfma_f32_32x32x16_bf16 v[48:63], v[208:211], v[148:151], v[48:63]
	ds_read_b128 v[208:211], v186 offset:24576
	s_waitcnt lgkmcnt(5)
	v_mfma_f32_32x32x16_bf16 v[32:47], v[212:215], v[148:151], v[32:47]
	ds_read_b128 v[212:215], v186 offset:28672
	s_waitcnt lgkmcnt(5)
	v_mfma_f32_32x32x16_bf16 v[16:31], v[216:219], v[148:151], v[16:31]
	ds_read_b128 v[216:219], v189 offset:16384
	s_waitcnt lgkmcnt(5)
	v_mfma_f32_32x32x16_bf16 v[0:15], v[220:223], v[148:151], v[0:15]
	ds_read_b128 v[220:223], v189 offset:20480
	s_waitcnt lgkmcnt(5)
	v_mfma_f32_32x32x16_bf16 v[48:63], v[224:227], v[152:155], v[48:63]
	ds_read_b128 v[224:227], v189 offset:24576
	s_waitcnt lgkmcnt(5)
	v_mfma_f32_32x32x16_bf16 v[32:47], v[228:231], v[152:155], v[32:47]
	ds_read_b128 v[228:231], v189 offset:28672
	s_waitcnt lgkmcnt(5)
	v_mfma_f32_32x32x16_bf16 v[16:31], v[208:211], v[152:155], v[16:31]
	ds_read_b128 v[208:211], v182 offset:49152
	s_waitcnt lgkmcnt(5)
	v_mfma_f32_32x32x16_bf16 v[0:15], v[212:215], v[152:155], v[0:15]
	ds_read_b128 v[212:215], v182 offset:53248
	s_waitcnt lgkmcnt(5)
	v_mfma_f32_32x32x16_bf16 v[48:63], v[216:219], v[156:159], v[48:63]
	ds_read_b128 v[216:219], v183 offset:49152
	s_waitcnt lgkmcnt(5)
	v_mfma_f32_32x32x16_bf16 v[32:47], v[220:223], v[156:159], v[32:47]
	ds_read_b128 v[220:223], v183 offset:53248
	s_waitcnt lgkmcnt(5)
	v_mfma_f32_32x32x16_bf16 v[16:31], v[224:227], v[156:159], v[16:31]
	ds_read_b128 v[224:227], v184 offset:49152
	s_waitcnt lgkmcnt(5)
	v_mfma_f32_32x32x16_bf16 v[0:15], v[228:231], v[156:159], v[0:15]
	ds_read_b128 v[228:231], v184 offset:53248
	s_waitcnt lgkmcnt(5)
	v_mfma_f32_32x32x16_bf16 v[96:111], v[208:211], v[128:131], 0
	ds_read_b128 v[208:211], v185 offset:49152
	s_waitcnt lgkmcnt(5)
	v_mfma_f32_32x32x16_bf16 v[112:127], v[212:215], v[128:131], 0
	ds_read_b128 v[212:215], v185 offset:53248
	s_waitcnt lgkmcnt(5)
	v_mfma_f32_32x32x16_bf16 v[96:111], v[216:219], v[132:135], v[96:111]
	s_waitcnt lgkmcnt(4)
	v_mfma_f32_32x32x16_bf16 v[112:127], v[220:223], v[132:135], v[112:127]
	s_waitcnt lgkmcnt(3)
	v_mfma_f32_32x32x16_bf16 v[96:111], v[224:227], v[136:139], v[96:111]
	s_waitcnt lgkmcnt(2)
	v_mfma_f32_32x32x16_bf16 v[112:127], v[228:231], v[136:139], v[112:127]
	s_waitcnt lgkmcnt(1)
	v_mfma_f32_32x32x16_bf16 v[96:111], v[208:211], v[140:143], v[96:111]
	s_waitcnt lgkmcnt(0)
	v_mfma_f32_32x32x16_bf16 v[112:127], v[212:215], v[140:143], v[112:127]
	s_cmp_lg_u32 s14, 0
	s_cbranch_scc0 .Lattn_tb6
	s_waitcnt vmcnt(4)
	s_barrier
.Lattn_tb6:
	ds_read_b128 v[216:219], v187 offset:32768
	ds_read_b128 v[220:223], v187 offset:36864
	ds_read_b128 v[224:227], v187 offset:40960
	ds_read_b128 v[228:231], v187 offset:45056
	ds_read_b128 v[208:211], v188 offset:32768
	ds_read_b128 v[212:215], v188 offset:36864
	v_exp_f32_e32 v171, v64
	v_exp_f32_e32 v173, v65
	v_exp_f32_e32 v179, v66
	s_add_i32 s2, s42, 5
	v_exp_f32_e32 v180, v67
	v_exp_f32_e32 v232, v68
	v_exp_f32_e32 v233, v69
	s_and_b32 s2, s2, 31
	v_exp_f32_e32 v234, v70
	v_exp_f32_e32 v235, v71
	v_add_f32_e32 v190, v171, v173
	s_mul_i32 s2, s2, 0x44000
	v_add_f32_e32 v191, v179, v180
	v_add_f32_e32 v190, v190, v232
	v_add_f32_e32 v191, v191, v233
	s_add_i32 m0, s5, 32768
	v_add_f32_e32 v190, v190, v234
	v_add_f32_e32 v191, v191, v235
	v_cvt_pk_bf16_f32 v144, v171, v173
	s_add_u32 s40, s26, s2
	v_cvt_pk_bf16_f32 v145, v179, v180
	v_cvt_pk_bf16_f32 v146, v232, v233
	v_cvt_pk_bf16_f32 v147, v234, v235
	s_addc_u32 s41, s27, 0
	v_exp_f32_e32 v171, v72
	v_exp_f32_e32 v173, v73
	v_exp_f32_e32 v179, v74
	global_load_lds_dwordx4 v170, s[40:41]
	v_exp_f32_e32 v180, v75
	v_exp_f32_e32 v232, v76
	v_exp_f32_e32 v233, v77
	s_add_i32 m0, s5, 40960
	v_exp_f32_e32 v234, v78
	v_exp_f32_e32 v235, v79
	v_add_f32_e32 v190, v190, v171
	s_add_u32 s40, s40, 0x80
	v_add_f32_e32 v191, v191, v173
	v_add_f32_e32 v190, v190, v179
	v_add_f32_e32 v191, v191, v180
	s_addc_u32 s41, s41, 0
	v_add_f32_e32 v190, v190, v232
	v_add_f32_e32 v191, v191, v233
	v_add_f32_e32 v190, v190, v234
	global_load_lds_dwordx4 v170, s[40:41]
	v_add_f32_e32 v191, v191, v235
	v_cvt_pk_bf16_f32 v148, v171, v173
	v_cvt_pk_bf16_f32 v149, v179, v180
	s_add_i32 s2, s42, 3
	v_cvt_pk_bf16_f32 v150, v232, v233
	v_cvt_pk_bf16_f32 v151, v234, v235
	v_exp_f32_e32 v171, v80
	s_and_b32 s2, s2, 31
	v_exp_f32_e32 v173, v81
	v_exp_f32_e32 v179, v82
	v_exp_f32_e32 v180, v83
	s_lshl_b32 s2, s2, 7
	v_exp_f32_e32 v232, v84
	v_exp_f32_e32 v233, v85
	v_exp_f32_e32 v234, v86
	s_add_i32 m0, s5, 65536
	v_exp_f32_e32 v235, v87
	v_add_f32_e32 v190, v190, v171
	v_add_f32_e32 v191, v191, v173
	s_add_u32 s44, s10, s2
	v_add_f32_e32 v190, v190, v179
	v_add_f32_e32 v191, v191, v180
	v_add_f32_e32 v190, v190, v232
	s_addc_u32 s45, s11, 0
	v_add_f32_e32 v191, v191, v233
	v_add_f32_e32 v190, v190, v234
	v_add_f32_e32 v191, v191, v235
	global_load_lds_dwordx4 v172, s[44:45]
	v_cvt_pk_bf16_f32 v152, v171, v173
	v_cvt_pk_bf16_f32 v153, v179, v180
	v_cvt_pk_bf16_f32 v154, v232, v233
	s_add_i32 m0, s5, 73728
	v_cvt_pk_bf16_f32 v155, v234, v235
	v_exp_f32_e32 v171, v88
	v_exp_f32_e32 v173, v89
	s_add_u32 s44, s44, 0x204000
	v_exp_f32_e32 v179, v90
	v_exp_f32_e32 v180, v91
	v_exp_f32_e32 v232, v92
	s_addc_u32 s45, s45, 0
	v_exp_f32_e32 v233, v93
	v_exp_f32_e32 v234, v94
	v_exp_f32_e32 v235, v95
	global_load_lds_dwordx4 v172, s[44:45]
	v_add_f32_e32 v190, v190, v171
	v_add_f32_e32 v191, v191, v173
	v_add_f32_e32 v190, v190, v179
	v_add_f32_e32 v191, v191, v180
	v_add_f32_e32 v190, v190, v232
	v_add_f32_e32 v191, v191, v233
	v_add_f32_e32 v190, v190, v234
	v_add_f32_e32 v191, v191, v235
	v_cvt_pk_bf16_f32 v156, v171, v173
	v_cvt_pk_bf16_f32 v157, v179, v180
	v_cvt_pk_bf16_f32 v158, v232, v233
	v_cvt_pk_bf16_f32 v159, v234, v235
	v_add_f32_e32 v190, v190, v191
	v_cmp_ngt_f32_e32 vcc, 0x71800000, v190
	s_nop 4
	s_cbranch_vccnz .Lattn_redo_L1
	v_add_f32_e32 v167, v167, v190
	s_cmp_lg_u32 s14, 0
	s_cbranch_scc1 .Lattn_tb7
	s_waitcnt vmcnt(4)
	s_barrier
.Lattn_tb7:
	s_waitcnt lgkmcnt(5)
	v_mfma_f32_32x32x16_bf16 v[48:63], v[216:219], v[144:147], v[48:63]
	ds_read_b128 v[216:219], v188 offset:40960
	s_waitcnt lgkmcnt(5)
	v_mfma_f32_32x32x16_bf16 v[32:47], v[220:223], v[144:147], v[32:47]
	ds_read_b128 v[220:223], v188 offset:45056
	s_waitcnt lgkmcnt(5)
	v_mfma_f32_32x32x16_bf16 v[16:31], v[224:227], v[144:147], v[16:31]
	ds_read_b128 v[224:227], v186 offset:32768
	s_waitcnt lgkmcnt(5)
	v_mfma_f32_32x32x16_bf16 v[0:15], v[228:231], v[144:147], v[0:15]
	ds_read_b128 v[228:231], v186 offset:36864
	s_waitcnt lgkmcnt(5)
	v_mfma_f32_32x32x16_bf16 v[48:63], v[208:211], v[148:151], v[48:63]
	ds_read_b128 v[208:211], v186 offset:40960
	s_waitcnt lgkmcnt(5)
	v_mfma_f32_32x32x16_bf16 v[32:47], v[212:215], v[148:151], v[32:47]
	ds_read_b128 v[212:215], v186 offset:45056
	s_waitcnt lgkmcnt(5)
	v_mfma_f32_32x32x16_bf16 v[16:31], v[216:219], v[148:151], v[16:31]
	ds_read_b128 v[216:219], v189 offset:32768
	s_waitcnt lgkmcnt(5)
	v_mfma_f32_32x32x16_bf16 v[0:15], v[220:223], v[148:151], v[0:15]
	ds_read_b128 v[220:223], v189 offset:36864
	s_waitcnt lgkmcnt(5)
	v_mfma_f32_32x32x16_bf16 v[48:63], v[224:227], v[152:155], v[48:63]
	ds_read_b128 v[224:227], v189 offset:40960
	s_waitcnt lgkmcnt(5)
	v_mfma_f32_32x32x16_bf16 v[32:47], v[228:231], v[152:155], v[32:47]
	ds_read_b128 v[228:231], v189 offset:45056
	s_waitcnt lgkmcnt(5)
	v_mfma_f32_32x32x16_bf16 v[16:31], v[208:211], v[152:155], v[16:31]
	ds_read_b128 v[208:211], v182 offset:0
	s_waitcnt lgkmcnt(5)
	v_mfma_f32_32x32x16_bf16 v[0:15], v[212:215], v[152:155], v[0:15]
	ds_read_b128 v[212:215], v182 offset:4096
	s_waitcnt lgkmcnt(5)
	v_mfma_f32_32x32x16_bf16 v[48:63], v[216:219], v[156:159], v[48:63]
	ds_read_b128 v[216:219], v183 offset:0
	s_waitcnt lgkmcnt(5)
	v_mfma_f32_32x32x16_bf16 v[32:47], v[220:223], v[156:159], v[32:47]
	ds_read_b128 v[220:223], v183 offset:4096
	s_waitcnt lgkmcnt(5)
	v_mfma_f32_32x32x16_bf16 v[16:31], v[224:227], v[156:159], v[16:31]
	ds_read_b128 v[224:227], v184 offset:0
	s_waitcnt lgkmcnt(5)
	v_mfma_f32_32x32x16_bf16 v[0:15], v[228:231], v[156:159], v[0:15]
	ds_read_b128 v[228:231], v184 offset:4096
	s_waitcnt lgkmcnt(5)
	v_mfma_f32_32x32x16_bf16 v[64:79], v[208:211], v[128:131], 0
	ds_read_b128 v[208:211], v185 offset:0
	s_waitcnt lgkmcnt(5)
	v_mfma_f32_32x32x16_bf16 v[80:95], v[212:215], v[128:131], 0
	ds_read_b128 v[212:215], v185 offset:4096
	s_waitcnt lgkmcnt(5)
	v_mfma_f32_32x32x16_bf16 v[64:79], v[216:219], v[132:135], v[64:79]
	s_waitcnt lgkmcnt(4)
	v_mfma_f32_32x32x16_bf16 v[80:95], v[220:223], v[132:135], v[80:95]
	s_waitcnt lgkmcnt(3)
	v_mfma_f32_32x32x16_bf16 v[64:79], v[224:227], v[136:139], v[64:79]
	s_waitcnt lgkmcnt(2)
	v_mfma_f32_32x32x16_bf16 v[80:95], v[228:231], v[136:139], v[80:95]
	s_waitcnt lgkmcnt(1)
	v_mfma_f32_32x32x16_bf16 v[64:79], v[208:211], v[140:143], v[64:79]
	s_waitcnt lgkmcnt(0)
	v_mfma_f32_32x32x16_bf16 v[80:95], v[212:215], v[140:143], v[80:95]
	s_cmp_lg_u32 s14, 0
	s_cbranch_scc0 .Lattn_tb8
	s_waitcnt vmcnt(4)
	s_barrier
.Lattn_tb8:
	ds_read_b128 v[216:219], v187 offset:49152
	ds_read_b128 v[220:223], v187 offset:53248
	ds_read_b128 v[224:227], v187 offset:57344
	ds_read_b128 v[228:231], v187 offset:61440
	ds_read_b128 v[208:211], v188 offset:49152
	ds_read_b128 v[212:215], v188 offset:53248
	v_exp_f32_e32 v171, v96
	v_exp_f32_e32 v173, v97
	v_exp_f32_e32 v179, v98
	s_add_i32 s2, s42, 6
	v_exp_f32_e32 v180, v99
	v_exp_f32_e32 v232, v100
	v_exp_f32_e32 v233, v101
	s_and_b32 s2, s2, 31
	v_exp_f32_e32 v234, v102
	v_exp_f32_e32 v235, v103
	v_add_f32_e32 v190, v171, v173
	s_mul_i32 s2, s2, 0x44000
	v_add_f32_e32 v191, v179, v180
	v_add_f32_e32 v190, v190, v232
	v_add_f32_e32 v191, v191, v233
	s_add_i32 m0, s5, 49152
	v_add_f32_e32 v190, v190, v234
	v_add_f32_e32 v191, v191, v235
	v_cvt_pk_bf16_f32 v144, v171, v173
	s_add_u32 s40, s26, s2
	v_cvt_pk_bf16_f32 v145, v179, v180
	v_cvt_pk_bf16_f32 v146, v232, v233
	v_cvt_pk_bf16_f32 v147, v234, v235
	s_addc_u32 s41, s27, 0
	v_exp_f32_e32 v171, v104
	v_exp_f32_e32 v173, v105
	v_exp_f32_e32 v179, v106
	global_load_lds_dwordx4 v170, s[40:41]
	v_exp_f32_e32 v180, v107
	v_exp_f32_e32 v232, v108
	v_exp_f32_e32 v233, v109
	s_add_i32 m0, s5, 57344
	v_exp_f32_e32 v234, v110
	v_exp_f32_e32 v235, v111
	v_add_f32_e32 v190, v190, v171
	s_add_u32 s40, s40, 0x80
	v_add_f32_e32 v191, v191, v173
	v_add_f32_e32 v190, v190, v179
	v_add_f32_e32 v191, v191, v180
	s_addc_u32 s41, s41, 0
	v_add_f32_e32 v190, v190, v232
	v_add_f32_e32 v191, v191, v233
	v_add_f32_e32 v190, v190, v234
	global_load_lds_dwordx4 v170, s[40:41]
	v_add_f32_e32 v191, v191, v235
	v_cvt_pk_bf16_f32 v148, v171, v173
	v_cvt_pk_bf16_f32 v149, v179, v180
	s_add_i32 s2, s42, 4
	v_cvt_pk_bf16_f32 v150, v232, v233
	v_cvt_pk_bf16_f32 v151, v234, v235
	v_exp_f32_e32 v171, v112
	s_and_b32 s2, s2, 31
	v_exp_f32_e32 v173, v113
	v_exp_f32_e32 v179, v114
	v_exp_f32_e32 v180, v115
	s_lshl_b32 s2, s2, 7
	v_exp_f32_e32 v232, v116
	v_exp_f32_e32 v233, v117
	v_exp_f32_e32 v234, v118
	s_add_i32 m0, s5, 81920
	v_exp_f32_e32 v235, v119
	v_add_f32_e32 v190, v190, v171
	v_add_f32_e32 v191, v191, v173
	s_add_u32 s44, s10, s2
	v_add_f32_e32 v190, v190, v179
	v_add_f32_e32 v191, v191, v180
	v_add_f32_e32 v190, v190, v232
	s_addc_u32 s45, s11, 0
	v_add_f32_e32 v191, v191, v233
	v_add_f32_e32 v190, v190, v234
	v_add_f32_e32 v191, v191, v235
	global_load_lds_dwordx4 v172, s[44:45]
	v_cvt_pk_bf16_f32 v152, v171, v173
	v_cvt_pk_bf16_f32 v153, v179, v180
	v_cvt_pk_bf16_f32 v154, v232, v233
	s_add_i32 m0, s5, 90112
	v_cvt_pk_bf16_f32 v155, v234, v235
	v_exp_f32_e32 v171, v120
	v_exp_f32_e32 v173, v121
	s_add_u32 s44, s44, 0x204000
	v_exp_f32_e32 v179, v122
	v_exp_f32_e32 v180, v123
	v_exp_f32_e32 v232, v124
	s_addc_u32 s45, s45, 0
	v_exp_f32_e32 v233, v125
	v_exp_f32_e32 v234, v126
	v_exp_f32_e32 v235, v127
	global_load_lds_dwordx4 v172, s[44:45]
	v_add_f32_e32 v190, v190, v171
	v_add_f32_e32 v191, v191, v173
	v_add_f32_e32 v190, v190, v179
	v_add_f32_e32 v191, v191, v180
	v_add_f32_e32 v190, v190, v232
	v_add_f32_e32 v191, v191, v233
	v_add_f32_e32 v190, v190, v234
	v_add_f32_e32 v191, v191, v235
	v_cvt_pk_bf16_f32 v156, v171, v173
	v_cvt_pk_bf16_f32 v157, v179, v180
	v_cvt_pk_bf16_f32 v158, v232, v233
	v_cvt_pk_bf16_f32 v159, v234, v235
	v_add_f32_e32 v190, v190, v191
	v_cmp_ngt_f32_e32 vcc, 0x71800000, v190
	s_nop 4
	s_cbranch_vccnz .Lattn_redo_L2
	v_add_f32_e32 v167, v167, v190
	s_cmp_lg_u32 s14, 0
	s_cbranch_scc1 .Lattn_tb9
	s_waitcnt vmcnt(4)
	s_barrier
.Lattn_tb9:
	s_waitcnt lgkmcnt(5)
	v_mfma_f32_32x32x16_bf16 v[48:63], v[216:219], v[144:147], v[48:63]
	ds_read_b128 v[216:219], v188 offset:57344
	s_waitcnt lgkmcnt(5)
	v_mfma_f32_32x32x16_bf16 v[32:47], v[220:223], v[144:147], v[32:47]
	ds_read_b128 v[220:223], v188 offset:61440
	s_waitcnt lgkmcnt(5)
	v_mfma_f32_32x32x16_bf16 v[16:31], v[224:227], v[144:147], v[16:31]
	ds_read_b128 v[224:227], v186 offset:49152
	s_waitcnt lgkmcnt(5)
	v_mfma_f32_32x32x16_bf16 v[0:15], v[228:231], v[144:147], v[0:15]
	ds_read_b128 v[228:231], v186 offset:53248
	s_waitcnt lgkmcnt(5)
	v_mfma_f32_32x32x16_bf16 v[48:63], v[208:211], v[148:151], v[48:63]
	ds_read_b128 v[208:211], v186 offset:57344
	s_waitcnt lgkmcnt(5)
	v_mfma_f32_32x32x16_bf16 v[32:47], v[212:215], v[148:151], v[32:47]
	ds_read_b128 v[212:215], v186 offset:61440
	s_waitcnt lgkmcnt(5)
	v_mfma_f32_32x32x16_bf16 v[16:31], v[216:219], v[148:151], v[16:31]
	ds_read_b128 v[216:219], v189 offset:49152
	s_waitcnt lgkmcnt(5)
	v_mfma_f32_32x32x16_bf16 v[0:15], v[220:223], v[148:151], v[0:15]
	ds_read_b128 v[220:223], v189 offset:53248
	s_waitcnt lgkmcnt(5)
	v_mfma_f32_32x32x16_bf16 v[48:63], v[224:227], v[152:155], v[48:63]
	ds_read_b128 v[224:227], v189 offset:57344
	s_waitcnt lgkmcnt(5)
	v_mfma_f32_32x32x16_bf16 v[32:47], v[228:231], v[152:155], v[32:47]
	ds_read_b128 v[228:231], v189 offset:61440
	s_waitcnt lgkmcnt(5)
	v_mfma_f32_32x32x16_bf16 v[16:31], v[208:211], v[152:155], v[16:31]
	ds_read_b128 v[208:211], v182 offset:16384
	s_waitcnt lgkmcnt(5)
	v_mfma_f32_32x32x16_bf16 v[0:15], v[212:215], v[152:155], v[0:15]
	ds_read_b128 v[212:215], v182 offset:20480
	s_waitcnt lgkmcnt(5)
	v_mfma_f32_32x32x16_bf16 v[48:63], v[216:219], v[156:159], v[48:63]
	ds_read_b128 v[216:219], v183 offset:16384
	s_waitcnt lgkmcnt(5)
	v_mfma_f32_32x32x16_bf16 v[32:47], v[220:223], v[156:159], v[32:47]
	ds_read_b128 v[220:223], v183 offset:20480
	s_waitcnt lgkmcnt(5)
	v_mfma_f32_32x32x16_bf16 v[16:31], v[224:227], v[156:159], v[16:31]
	ds_read_b128 v[224:227], v184 offset:16384
	s_waitcnt lgkmcnt(5)
	v_mfma_f32_32x32x16_bf16 v[0:15], v[228:231], v[156:159], v[0:15]
	ds_read_b128 v[228:231], v184 offset:20480
	s_waitcnt lgkmcnt(5)
	v_mfma_f32_32x32x16_bf16 v[96:111], v[208:211], v[128:131], 0
	ds_read_b128 v[208:211], v185 offset:16384
	s_waitcnt lgkmcnt(5)
	v_mfma_f32_32x32x16_bf16 v[112:127], v[212:215], v[128:131], 0
	ds_read_b128 v[212:215], v185 offset:20480
	s_waitcnt lgkmcnt(5)
	v_mfma_f32_32x32x16_bf16 v[96:111], v[216:219], v[132:135], v[96:111]
	s_waitcnt lgkmcnt(4)
	v_mfma_f32_32x32x16_bf16 v[112:127], v[220:223], v[132:135], v[112:127]
	s_waitcnt lgkmcnt(3)
	v_mfma_f32_32x32x16_bf16 v[96:111], v[224:227], v[136:139], v[96:111]
	s_waitcnt lgkmcnt(2)
	v_mfma_f32_32x32x16_bf16 v[112:127], v[228:231], v[136:139], v[112:127]
	s_waitcnt lgkmcnt(1)
	v_mfma_f32_32x32x16_bf16 v[96:111], v[208:211], v[140:143], v[96:111]
	s_waitcnt lgkmcnt(0)
	v_mfma_f32_32x32x16_bf16 v[112:127], v[212:215], v[140:143], v[112:127]
	s_cmp_lg_u32 s14, 0
	s_cbranch_scc0 .Lattn_tb10
	s_waitcnt vmcnt(4)
	s_barrier
.Lattn_tb10:
	ds_read_b128 v[216:219], v187 offset:0
	ds_read_b128 v[220:223], v187 offset:4096
	ds_read_b128 v[224:227], v187 offset:8192
	ds_read_b128 v[228:231], v187 offset:12288
	ds_read_b128 v[208:211], v188 offset:0
	ds_read_b128 v[212:215], v188 offset:4096
	v_exp_f32_e32 v171, v64
	v_exp_f32_e32 v173, v65
	v_exp_f32_e32 v179, v66
	s_add_i32 s2, s42, 7
	v_exp_f32_e32 v180, v67
	v_exp_f32_e32 v232, v68
	v_exp_f32_e32 v233, v69
	s_and_b32 s2, s2, 31
	v_exp_f32_e32 v234, v70
	v_exp_f32_e32 v235, v71
	v_add_f32_e32 v190, v171, v173
	s_mul_i32 s2, s2, 0x44000
	v_add_f32_e32 v191, v179, v180
	v_add_f32_e32 v190, v190, v232
	v_add_f32_e32 v191, v191, v233
	s_add_i32 m0, s5, 0
	v_add_f32_e32 v190, v190, v234
	v_add_f32_e32 v191, v191, v235
	v_cvt_pk_bf16_f32 v144, v171, v173
	s_add_u32 s40, s26, s2
	v_cvt_pk_bf16_f32 v145, v179, v180
	v_cvt_pk_bf16_f32 v146, v232, v233
	v_cvt_pk_bf16_f32 v147, v234, v235
	s_addc_u32 s41, s27, 0
	v_exp_f32_e32 v171, v72
	v_exp_f32_e32 v173, v73
	v_exp_f32_e32 v179, v74
	global_load_lds_dwordx4 v170, s[40:41]
	v_exp_f32_e32 v180, v75
	v_exp_f32_e32 v232, v76
	v_exp_f32_e32 v233, v77
	s_add_i32 m0, s5, 8192
	v_exp_f32_e32 v234, v78
	v_exp_f32_e32 v235, v79
	v_add_f32_e32 v190, v190, v171
	s_add_u32 s40, s40, 0x80
	v_add_f32_e32 v191, v191, v173
	v_add_f32_e32 v190, v190, v179
	v_add_f32_e32 v191, v191, v180
	s_addc_u32 s41, s41, 0
	v_add_f32_e32 v190, v190, v232
	v_add_f32_e32 v191, v191, v233
	v_add_f32_e32 v190, v190, v234
	global_load_lds_dwordx4 v170, s[40:41]
	v_add_f32_e32 v191, v191, v235
	v_cvt_pk_bf16_f32 v148, v171, v173
	v_cvt_pk_bf16_f32 v149, v179, v180
	s_add_i32 s2, s42, 5
	v_cvt_pk_bf16_f32 v150, v232, v233
	v_cvt_pk_bf16_f32 v151, v234, v235
	v_exp_f32_e32 v171, v80
	s_and_b32 s2, s2, 31
	v_exp_f32_e32 v173, v81
	v_exp_f32_e32 v179, v82
	v_exp_f32_e32 v180, v83
	s_lshl_b32 s2, s2, 7
	v_exp_f32_e32 v232, v84
	v_exp_f32_e32 v233, v85
	v_exp_f32_e32 v234, v86
	s_add_i32 m0, s5, 98304
	v_exp_f32_e32 v235, v87
	v_add_f32_e32 v190, v190, v171
	v_add_f32_e32 v191, v191, v173
	s_add_u32 s44, s10, s2
	v_add_f32_e32 v190, v190, v179
	v_add_f32_e32 v191, v191, v180
	v_add_f32_e32 v190, v190, v232
	s_addc_u32 s45, s11, 0
	v_add_f32_e32 v191, v191, v233
	v_add_f32_e32 v190, v190, v234
	v_add_f32_e32 v191, v191, v235
	global_load_lds_dwordx4 v172, s[44:45]
	v_cvt_pk_bf16_f32 v152, v171, v173
	v_cvt_pk_bf16_f32 v153, v179, v180
	v_cvt_pk_bf16_f32 v154, v232, v233
	s_add_i32 m0, s5, 106496
	v_cvt_pk_bf16_f32 v155, v234, v235
	v_exp_f32_e32 v171, v88
	v_exp_f32_e32 v173, v89
	s_add_u32 s44, s44, 0x204000
	v_exp_f32_e32 v179, v90
	v_exp_f32_e32 v180, v91
	v_exp_f32_e32 v232, v92
	s_addc_u32 s45, s45, 0
	v_exp_f32_e32 v233, v93
	v_exp_f32_e32 v234, v94
	v_exp_f32_e32 v235, v95
	global_load_lds_dwordx4 v172, s[44:45]
	v_add_f32_e32 v190, v190, v171
	v_add_f32_e32 v191, v191, v173
	v_add_f32_e32 v190, v190, v179
	v_add_f32_e32 v191, v191, v180
	v_add_f32_e32 v190, v190, v232
	v_add_f32_e32 v191, v191, v233
	v_add_f32_e32 v190, v190, v234
	v_add_f32_e32 v191, v191, v235
	v_cvt_pk_bf16_f32 v156, v171, v173
	v_cvt_pk_bf16_f32 v157, v179, v180
	v_cvt_pk_bf16_f32 v158, v232, v233
	v_cvt_pk_bf16_f32 v159, v234, v235
	v_add_f32_e32 v190, v190, v191
	v_cmp_ngt_f32_e32 vcc, 0x71800000, v190
	s_nop 4
	s_cbranch_vccnz .Lattn_redo_L3
	v_add_f32_e32 v167, v167, v190
	s_add_i32 s42, s42, 4
	s_add_i32 s47, s47, -1
	s_cmp_lg_u32 s47, 0
	s_cbranch_scc1 .Lattn_loop_f
	s_cmp_lg_u32 s14, 0
	s_cbranch_scc1 .Lattn_tb11
	s_waitcnt vmcnt(4)
	s_barrier

.Lattn_tb12:
	ds_read_b128 v[216:219], v187 offset:16384
	ds_read_b128 v[220:223], v187 offset:20480
	ds_read_b128 v[224:227], v187 offset:24576
	ds_read_b128 v[228:231], v187 offset:28672
	ds_read_b128 v[208:211], v188 offset:16384
	ds_read_b128 v[212:215], v188 offset:20480
	v_exp_f32_e32 v171, v96
	v_exp_f32_e32 v173, v97
	v_exp_f32_e32 v179, v98
	s_add_i32 s2, s42, 2
	v_exp_f32_e32 v180, v99
	v_exp_f32_e32 v232, v100
	v_exp_f32_e32 v233, v101
	s_and_b32 s2, s2, 31
	v_exp_f32_e32 v234, v102
	v_exp_f32_e32 v235, v103
	v_add_f32_e32 v190, v171, v173
	s_lshl_b32 s2, s2, 7
	v_add_f32_e32 v191, v179, v180
	v_add_f32_e32 v190, v190, v232
	v_add_f32_e32 v191, v191, v233
	s_add_i32 m0, s5, 114688
	v_add_f32_e32 v190, v190, v234
	v_add_f32_e32 v191, v191, v235
	v_cvt_pk_bf16_f32 v144, v171, v173
	s_add_u32 s44, s10, s2
	v_cvt_pk_bf16_f32 v145, v179, v180
	v_cvt_pk_bf16_f32 v146, v232, v233
	v_cvt_pk_bf16_f32 v147, v234, v235
	s_addc_u32 s45, s11, 0
	v_exp_f32_e32 v171, v104
	v_exp_f32_e32 v173, v105
	v_exp_f32_e32 v179, v106
	global_load_lds_dwordx4 v172, s[44:45]
	v_exp_f32_e32 v180, v107
	v_exp_f32_e32 v232, v108
	v_exp_f32_e32 v233, v109
	s_add_i32 m0, s5, 122880
	v_exp_f32_e32 v234, v110
	v_exp_f32_e32 v235, v111
	v_add_f32_e32 v190, v190, v171
	s_add_u32 s44, s44, 0x204000
	v_add_f32_e32 v191, v191, v173
	v_add_f32_e32 v190, v190, v179
	v_add_f32_e32 v191, v191, v180
	s_addc_u32 s45, s45, 0
	v_add_f32_e32 v190, v190, v232
	v_add_f32_e32 v191, v191, v233
	v_add_f32_e32 v190, v190, v234
	global_load_lds_dwordx4 v172, s[44:45]
	v_add_f32_e32 v191, v191, v235
	v_cvt_pk_bf16_f32 v148, v171, v173
	v_cvt_pk_bf16_f32 v149, v179, v180
	v_cvt_pk_bf16_f32 v150, v232, v233
	v_cvt_pk_bf16_f32 v151, v234, v235
	v_exp_f32_e32 v171, v112
	v_exp_f32_e32 v173, v113
	v_exp_f32_e32 v179, v114
	v_exp_f32_e32 v180, v115
	v_exp_f32_e32 v232, v116
	v_exp_f32_e32 v233, v117
	v_exp_f32_e32 v234, v118
	v_exp_f32_e32 v235, v119
	v_add_f32_e32 v190, v190, v171
	v_add_f32_e32 v191, v191, v173
	v_add_f32_e32 v190, v190, v179
	v_add_f32_e32 v191, v191, v180
	v_add_f32_e32 v190, v190, v232
	v_add_f32_e32 v191, v191, v233
	v_add_f32_e32 v190, v190, v234
	v_add_f32_e32 v191, v191, v235
	v_cvt_pk_bf16_f32 v152, v171, v173
	v_cvt_pk_bf16_f32 v153, v179, v180
	v_cvt_pk_bf16_f32 v154, v232, v233
	v_cvt_pk_bf16_f32 v155, v234, v235
	v_exp_f32_e32 v171, v120
	v_exp_f32_e32 v173, v121
	v_exp_f32_e32 v179, v122
	v_exp_f32_e32 v180, v123
	v_exp_f32_e32 v232, v124
	v_exp_f32_e32 v233, v125
	v_exp_f32_e32 v234, v126
	v_exp_f32_e32 v235, v127
	v_add_f32_e32 v190, v190, v171
	v_add_f32_e32 v191, v191, v173
	v_add_f32_e32 v190, v190, v179
	v_add_f32_e32 v191, v191, v180
	v_add_f32_e32 v190, v190, v232
	v_add_f32_e32 v191, v191, v233
	v_add_f32_e32 v190, v190, v234
	v_add_f32_e32 v191, v191, v235
	v_cvt_pk_bf16_f32 v156, v171, v173
	v_cvt_pk_bf16_f32 v157, v179, v180
	v_cvt_pk_bf16_f32 v158, v232, v233
	v_cvt_pk_bf16_f32 v159, v234, v235
	v_add_f32_e32 v190, v190, v191
	v_cmp_ngt_f32_e32 vcc, 0x71800000, v190
	s_nop 4
	s_cbranch_vccnz .Lattn_redo_T29
	v_add_f32_e32 v167, v167, v190
	s_cmp_lg_u32 s14, 0
	s_cbranch_scc1 .Lattn_tb13
	s_waitcnt vmcnt(2)
	s_barrier
.Lattn_tb13:
	s_waitcnt lgkmcnt(5)
	v_mfma_f32_32x32x16_bf16 v[48:63], v[216:219], v[144:147], v[48:63]
	ds_read_b128 v[216:219], v188 offset:24576
	s_waitcnt lgkmcnt(5)
	v_mfma_f32_32x32x16_bf16 v[32:47], v[220:223], v[144:147], v[32:47]
	ds_read_b128 v[220:223], v188 offset:28672
	s_waitcnt lgkmcnt(5)
	v_mfma_f32_32x32x16_bf16 v[16:31], v[224:227], v[144:147], v[16:31]
	ds_read_b128 v[224:227], v186 offset:16384
	s_waitcnt lgkmcnt(5)
	v_mfma_f32_32x32x16_bf16 v[0:15], v[228:231], v[144:147], v[0:15]
	ds_read_b128 v[228:231], v186 offset:20480
	s_waitcnt lgkmcnt(5)
	v_mfma_f32_32x32x16_bf16 v[48:63], v[208:211], v[148:151], v[48:63]
	ds_read_b128 v[208:211], v186 offset:24576
	s_waitcnt lgkmcnt(5)
	v_mfma_f32_32x32x16_bf16 v[32:47], v[212:215], v[148:151], v[32:47]
	ds_read_b128 v[212:215], v186 offset:28672
	s_waitcnt lgkmcnt(5)
	v_mfma_f32_32x32x16_bf16 v[16:31], v[216:219], v[148:151], v[16:31]
	ds_read_b128 v[216:219], v189 offset:16384
	s_waitcnt lgkmcnt(5)
	v_mfma_f32_32x32x16_bf16 v[0:15], v[220:223], v[148:151], v[0:15]
	ds_read_b128 v[220:223], v189 offset:20480
	s_waitcnt lgkmcnt(5)
	v_mfma_f32_32x32x16_bf16 v[48:63], v[224:227], v[152:155], v[48:63]
	ds_read_b128 v[224:227], v189 offset:24576
	s_waitcnt lgkmcnt(5)
	v_mfma_f32_32x32x16_bf16 v[32:47], v[228:231], v[152:155], v[32:47]
	ds_read_b128 v[228:231], v189 offset:28672
	s_waitcnt lgkmcnt(5)
	v_mfma_f32_32x32x16_bf16 v[16:31], v[208:211], v[152:155], v[16:31]
	ds_read_b128 v[208:211], v182 offset:49152
	s_waitcnt lgkmcnt(5)
	v_mfma_f32_32x32x16_bf16 v[0:15], v[212:215], v[152:155], v[0:15]
	ds_read_b128 v[212:215], v182 offset:53248
	s_waitcnt lgkmcnt(5)
	v_mfma_f32_32x32x16_bf16 v[48:63], v[216:219], v[156:159], v[48:63]
	ds_read_b128 v[216:219], v183 offset:49152
	s_waitcnt lgkmcnt(5)
	v_mfma_f32_32x32x16_bf16 v[32:47], v[220:223], v[156:159], v[32:47]
	ds_read_b128 v[220:223], v183 offset:53248
	s_waitcnt lgkmcnt(5)
	v_mfma_f32_32x32x16_bf16 v[16:31], v[224:227], v[156:159], v[16:31]
	ds_read_b128 v[224:227], v184 offset:49152
	s_waitcnt lgkmcnt(5)
	v_mfma_f32_32x32x16_bf16 v[0:15], v[228:231], v[156:159], v[0:15]
	ds_read_b128 v[228:231], v184 offset:53248
	s_waitcnt lgkmcnt(5)
	v_mfma_f32_32x32x16_bf16 v[96:111], v[208:211], v[128:131], 0
	ds_read_b128 v[208:211], v185 offset:49152
	s_waitcnt lgkmcnt(5)
	v_mfma_f32_32x32x16_bf16 v[112:127], v[212:215], v[128:131], 0
	ds_read_b128 v[212:215], v185 offset:53248
	s_waitcnt lgkmcnt(5)
	v_mfma_f32_32x32x16_bf16 v[96:111], v[216:219], v[132:135], v[96:111]
	s_waitcnt lgkmcnt(4)
	v_mfma_f32_32x32x16_bf16 v[112:127], v[220:223], v[132:135], v[112:127]
	s_waitcnt lgkmcnt(3)
	v_mfma_f32_32x32x16_bf16 v[96:111], v[224:227], v[136:139], v[96:111]
	s_waitcnt lgkmcnt(2)
	v_mfma_f32_32x32x16_bf16 v[112:127], v[228:231], v[136:139], v[112:127]
	s_waitcnt lgkmcnt(1)
	v_mfma_f32_32x32x16_bf16 v[96:111], v[208:211], v[140:143], v[96:111]
	s_waitcnt lgkmcnt(0)
	v_mfma_f32_32x32x16_bf16 v[112:127], v[212:215], v[140:143], v[112:127]
	s_cmp_lg_u32 s14, 0
	s_cbranch_scc0 .Lattn_tb14
	s_waitcnt vmcnt(2)
	s_barrier
.Lattn_tb14:
	ds_read_b128 v[216:219], v187 offset:32768
	ds_read_b128 v[220:223], v187 offset:36864
	ds_read_b128 v[224:227], v187 offset:40960
	ds_read_b128 v[228:231], v187 offset:45056
	ds_read_b128 v[208:211], v188 offset:32768
	ds_read_b128 v[212:215], v188 offset:36864
	v_exp_f32_e32 v171, v64
	v_exp_f32_e32 v173, v65
	v_exp_f32_e32 v179, v66
	v_readlane_b32 s2, v253, 52
	s_add_i32 s36, s46, 1
	s_mul_i32 s36, s36, s56
	s_add_i32 s36, s36, s0
	s_cmp_lg_u32 s2, 0
	s_cselect_b32 s2, 1, 0
	s_cmpk_lt_i32 s36, 0x400
	s_cselect_b32 s36, 1, 0
	s_and_b32 s35, s2, s36
	v_exp_f32_e32 v180, v67
	v_exp_f32_e32 v232, v68
	v_exp_f32_e32 v233, v69
	s_cmp_lg_u32 s35, 0
	s_cbranch_scc0 .Lattn_pfka_f
	s_add_i32 s2, s31, 0
	s_and_b32 s2, s2, 31
	s_mul_i32 s2, s2, 0x44000
	s_add_i32 m0, s5, 0
	s_add_u32 s40, s26, s2
	s_addc_u32 s41, s27, 0
	s_add_u32 s40, s40, 0x1100000
	s_addc_u32 s41, s41, 0
	global_load_lds_dwordx4 v170, s[40:41]
	s_add_i32 m0, s5, 8192
	s_add_u32 s40, s40, 0x80
	s_addc_u32 s41, s41, 0
	global_load_lds_dwordx4 v170, s[40:41]
.Lattn_pfka_f:
	v_exp_f32_e32 v234, v70
	v_exp_f32_e32 v235, v71
	v_add_f32_e32 v190, v171, v173
	s_cmp_lg_u32 s35, 0
	s_cbranch_scc0 .Lattn_pfkb_f
	s_add_i32 s2, s31, 1
	s_and_b32 s2, s2, 31
	s_mul_i32 s2, s2, 0x44000
	s_add_i32 m0, s5, 16384
	s_add_u32 s40, s26, s2
	s_addc_u32 s41, s27, 0
	s_add_u32 s40, s40, 0x1100000
	s_addc_u32 s41, s41, 0
	global_load_lds_dwordx4 v170, s[40:41]
	s_add_i32 m0, s5, 24576
	s_add_u32 s40, s40, 0x80
	s_addc_u32 s41, s41, 0
	global_load_lds_dwordx4 v170, s[40:41]
.Lattn_pfkb_f:
	v_add_f32_e32 v191, v179, v180
	v_add_f32_e32 v190, v190, v232
	v_add_f32_e32 v191, v191, v233
	s_cmp_lg_u32 s35, 0
	s_cbranch_scc0 .Lattn_pfvt_f
	s_add_i32 s2, s31, 0
	s_and_b32 s2, s2, 31
	s_lshl_b32 s2, s2, 7
	s_add_i32 m0, s5, 65536
	s_add_u32 s44, s10, s2
	s_addc_u32 s45, s11, 0
	s_add_u32 s44, s44, 0x2000
	s_addc_u32 s45, s45, 0
	global_load_lds_dwordx4 v172, s[44:45]
	s_add_i32 m0, s5, 73728
	s_add_u32 s44, s44, 0x204000
	s_addc_u32 s45, s45, 0
	global_load_lds_dwordx4 v172, s[44:45]
.Lattn_pfvt_f:
	v_add_f32_e32 v190, v190, v234
	v_add_f32_e32 v191, v191, v235
	v_cvt_pk_bf16_f32 v144, v171, v173
	v_cvt_pk_bf16_f32 v145, v179, v180
	v_cvt_pk_bf16_f32 v146, v232, v233
	v_cvt_pk_bf16_f32 v147, v234, v235
	v_exp_f32_e32 v171, v72
	v_exp_f32_e32 v173, v73
	v_exp_f32_e32 v179, v74
	v_exp_f32_e32 v180, v75
	v_exp_f32_e32 v232, v76
	v_exp_f32_e32 v233, v77
	v_exp_f32_e32 v234, v78
	v_exp_f32_e32 v235, v79
	v_add_f32_e32 v190, v190, v171
	v_add_f32_e32 v191, v191, v173
	v_add_f32_e32 v190, v190, v179
	v_add_f32_e32 v191, v191, v180
	v_add_f32_e32 v190, v190, v232
	v_add_f32_e32 v191, v191, v233
	v_add_f32_e32 v190, v190, v234
	v_add_f32_e32 v191, v191, v235
	v_cvt_pk_bf16_f32 v148, v171, v173
	v_cvt_pk_bf16_f32 v149, v179, v180
	v_cvt_pk_bf16_f32 v150, v232, v233
	v_cvt_pk_bf16_f32 v151, v234, v235
	v_exp_f32_e32 v171, v80
	v_exp_f32_e32 v173, v81
	v_exp_f32_e32 v179, v82
	v_exp_f32_e32 v180, v83
	v_exp_f32_e32 v232, v84
	v_exp_f32_e32 v233, v85
	v_exp_f32_e32 v234, v86
	v_exp_f32_e32 v235, v87
	v_add_f32_e32 v190, v190, v171
	v_add_f32_e32 v191, v191, v173
	v_add_f32_e32 v190, v190, v179
	v_add_f32_e32 v191, v191, v180
	v_add_f32_e32 v190, v190, v232
	v_add_f32_e32 v191, v191, v233
	v_add_f32_e32 v190, v190, v234
	v_add_f32_e32 v191, v191, v235
	v_cvt_pk_bf16_f32 v152, v171, v173
	v_cvt_pk_bf16_f32 v153, v179, v180
	v_cvt_pk_bf16_f32 v154, v232, v233
	v_cvt_pk_bf16_f32 v155, v234, v235
	v_exp_f32_e32 v171, v88
	v_exp_f32_e32 v173, v89
	v_exp_f32_e32 v179, v90
	v_exp_f32_e32 v180, v91
	v_exp_f32_e32 v232, v92
	v_exp_f32_e32 v233, v93
	v_exp_f32_e32 v234, v94
	v_exp_f32_e32 v235, v95
	v_add_f32_e32 v190, v190, v171
	v_add_f32_e32 v191, v191, v173
	v_add_f32_e32 v190, v190, v179
	v_add_f32_e32 v191, v191, v180
	v_add_f32_e32 v190, v190, v232
	v_add_f32_e32 v191, v191, v233
	v_add_f32_e32 v190, v190, v234
	v_add_f32_e32 v191, v191, v235
	v_cvt_pk_bf16_f32 v156, v171, v173
	v_cvt_pk_bf16_f32 v157, v179, v180
	v_cvt_pk_bf16_f32 v158, v232, v233
	v_cvt_pk_bf16_f32 v159, v234, v235
	v_add_f32_e32 v190, v190, v191
	v_cmp_ngt_f32_e32 vcc, 0x71800000, v190
	s_nop 4
	s_cbranch_vccnz .Lattn_redo_T30
	v_add_f32_e32 v167, v167, v190
	s_cmp_lg_u32 s14, 0
	s_cbranch_scc1 .Lattn_tb15
	s_cmp_lg_u32 s35, 0
	s_cbranch_scc1 .Lattn_tb15_w6
	s_waitcnt vmcnt(0)
	s_branch .Lattn_tb15_wd

.Lattn_tb15:
	s_waitcnt lgkmcnt(5)
	v_mfma_f32_32x32x16_bf16 v[48:63], v[216:219], v[144:147], v[48:63]
	ds_read_b128 v[216:219], v188 offset:40960
	s_waitcnt lgkmcnt(5)
	v_mfma_f32_32x32x16_bf16 v[32:47], v[220:223], v[144:147], v[32:47]
	ds_read_b128 v[220:223], v188 offset:45056
	s_waitcnt lgkmcnt(5)
	v_mfma_f32_32x32x16_bf16 v[16:31], v[224:227], v[144:147], v[16:31]
	ds_read_b128 v[224:227], v186 offset:32768
	s_waitcnt lgkmcnt(5)
	v_mfma_f32_32x32x16_bf16 v[0:15], v[228:231], v[144:147], v[0:15]
	ds_read_b128 v[228:231], v186 offset:36864
	s_waitcnt lgkmcnt(5)
	v_mfma_f32_32x32x16_bf16 v[48:63], v[208:211], v[148:151], v[48:63]
	ds_read_b128 v[208:211], v186 offset:40960
	s_waitcnt lgkmcnt(5)
	v_mfma_f32_32x32x16_bf16 v[32:47], v[212:215], v[148:151], v[32:47]
	ds_read_b128 v[212:215], v186 offset:45056
	s_waitcnt lgkmcnt(5)
	v_mfma_f32_32x32x16_bf16 v[16:31], v[216:219], v[148:151], v[16:31]
	ds_read_b128 v[216:219], v189 offset:32768
	s_waitcnt lgkmcnt(5)
	v_mfma_f32_32x32x16_bf16 v[0:15], v[220:223], v[148:151], v[0:15]
	ds_read_b128 v[220:223], v189 offset:36864
	s_waitcnt lgkmcnt(5)
	v_mfma_f32_32x32x16_bf16 v[48:63], v[224:227], v[152:155], v[48:63]
	ds_read_b128 v[224:227], v189 offset:40960
	s_waitcnt lgkmcnt(5)
	v_mfma_f32_32x32x16_bf16 v[32:47], v[228:231], v[152:155], v[32:47]
	ds_read_b128 v[228:231], v189 offset:45056
	s_waitcnt lgkmcnt(5)
	v_mfma_f32_32x32x16_bf16 v[16:31], v[208:211], v[152:155], v[16:31]
	s_waitcnt lgkmcnt(4)
	v_mfma_f32_32x32x16_bf16 v[0:15], v[212:215], v[152:155], v[0:15]
	s_waitcnt lgkmcnt(3)
	v_mfma_f32_32x32x16_bf16 v[48:63], v[216:219], v[156:159], v[48:63]
	s_waitcnt lgkmcnt(2)
	v_mfma_f32_32x32x16_bf16 v[32:47], v[220:223], v[156:159], v[32:47]
	s_waitcnt lgkmcnt(1)
	v_mfma_f32_32x32x16_bf16 v[16:31], v[224:227], v[156:159], v[16:31]
	s_waitcnt lgkmcnt(0)
	v_mfma_f32_32x32x16_bf16 v[0:15], v[228:231], v[156:159], v[0:15]
	s_cmp_lg_u32 s14, 0
	s_cbranch_scc0 .Lattn_tb16
	s_cmp_lg_u32 s35, 0
	s_cbranch_scc1 .Lattn_tb16_w6
	s_waitcnt vmcnt(0)
	s_branch .Lattn_tb16_wd

.Lattn_tb16:
	ds_read_b128 v[208:211], v187 offset:49152
	ds_read_b128 v[212:215], v187 offset:53248
	ds_read_b128 v[216:219], v187 offset:57344
	ds_read_b128 v[220:223], v187 offset:61440
	ds_read_b128 v[224:227], v188 offset:49152
	ds_read_b128 v[228:231], v188 offset:53248
	v_exp_f32_e32 v171, v96
	v_exp_f32_e32 v173, v97
	v_exp_f32_e32 v179, v98
	s_cmp_lg_u32 s35, 0
	s_cbranch_scc0 .Lattn_pfq_f
	s_movk_i32 s2, 0x1100
	s_lshl_b32 s36, s14, 1
	v_mad_u32_u24 v72, v168, s2, v192
	s_add_i32 s36, s36, s30
	s_add_i32 s36, s36, 0x1100000
	s_nop 0
	v_add_u32_e32 v72, s36, v72
	s_nop 0
	global_load_dwordx4 v[64:67], v72, s[6:7]
	global_load_dwordx4 v[68:71], v72, s[6:7] offset:32
	global_load_dwordx4 v[136:139], v72, s[6:7] offset:64
	global_load_dwordx4 v[140:143], v72, s[6:7] offset:96
.Lattn_pfq_f:
	v_exp_f32_e32 v180, v99
	v_exp_f32_e32 v232, v100
	v_exp_f32_e32 v233, v101
	v_exp_f32_e32 v234, v102
	v_exp_f32_e32 v235, v103
	v_add_f32_e32 v190, v171, v173
	v_add_f32_e32 v191, v179, v180
	v_add_f32_e32 v190, v190, v232
	v_add_f32_e32 v191, v191, v233
	v_add_f32_e32 v190, v190, v234
	v_add_f32_e32 v191, v191, v235
	v_cvt_pk_bf16_f32 v144, v171, v173
	v_cvt_pk_bf16_f32 v145, v179, v180
	v_cvt_pk_bf16_f32 v146, v232, v233
	v_cvt_pk_bf16_f32 v147, v234, v235
	v_exp_f32_e32 v171, v104
	v_exp_f32_e32 v173, v105
	v_exp_f32_e32 v179, v106
	v_exp_f32_e32 v180, v107
	v_exp_f32_e32 v232, v108
	v_exp_f32_e32 v233, v109
	v_exp_f32_e32 v234, v110
	v_exp_f32_e32 v235, v111
	v_add_f32_e32 v190, v190, v171
	v_add_f32_e32 v191, v191, v173
	v_add_f32_e32 v190, v190, v179
	v_add_f32_e32 v191, v191, v180
	v_add_f32_e32 v190, v190, v232
	v_add_f32_e32 v191, v191, v233
	v_add_f32_e32 v190, v190, v234
	v_add_f32_e32 v191, v191, v235
	v_cvt_pk_bf16_f32 v148, v171, v173
	v_cvt_pk_bf16_f32 v149, v179, v180
	v_cvt_pk_bf16_f32 v150, v232, v233
	v_cvt_pk_bf16_f32 v151, v234, v235
	v_exp_f32_e32 v171, v112
	v_exp_f32_e32 v173, v113
	v_exp_f32_e32 v179, v114
	v_exp_f32_e32 v180, v115
	v_exp_f32_e32 v232, v116
	v_exp_f32_e32 v233, v117
	v_exp_f32_e32 v234, v118
	v_exp_f32_e32 v235, v119
	v_add_f32_e32 v190, v190, v171
	v_add_f32_e32 v191, v191, v173
	v_add_f32_e32 v190, v190, v179
	v_add_f32_e32 v191, v191, v180
	v_add_f32_e32 v190, v190, v232
	v_add_f32_e32 v191, v191, v233
	v_add_f32_e32 v190, v190, v234
	v_add_f32_e32 v191, v191, v235
	v_cvt_pk_bf16_f32 v152, v171, v173
	v_cvt_pk_bf16_f32 v153, v179, v180
	v_cvt_pk_bf16_f32 v154, v232, v233
	v_cvt_pk_bf16_f32 v155, v234, v235
	v_exp_f32_e32 v171, v120
	v_exp_f32_e32 v173, v121
	v_exp_f32_e32 v179, v122
	v_exp_f32_e32 v180, v123
	v_exp_f32_e32 v232, v124
	v_exp_f32_e32 v233, v125
	v_exp_f32_e32 v234, v126
	v_exp_f32_e32 v235, v127
	v_add_f32_e32 v190, v190, v171
	v_add_f32_e32 v191, v191, v173
	v_add_f32_e32 v190, v190, v179
	v_add_f32_e32 v191, v191, v180
	v_add_f32_e32 v190, v190, v232
	v_add_f32_e32 v191, v191, v233
	v_add_f32_e32 v190, v190, v234
	v_add_f32_e32 v191, v191, v235
	v_cvt_pk_bf16_f32 v156, v171, v173
	v_cvt_pk_bf16_f32 v157, v179, v180
	v_cvt_pk_bf16_f32 v158, v232, v233
	v_cvt_pk_bf16_f32 v159, v234, v235
	v_add_f32_e32 v190, v190, v191
	v_cmp_ngt_f32_e32 vcc, 0x71800000, v190
	s_nop 4
	s_cbranch_vccnz .Lattn_redo_T31
	v_add_f32_e32 v167, v167, v190

.Lattn_top_t0:
	s_cmp_lg_u32 s14, 0
	s_cbranch_scc1 .Lattn_tb17
	s_barrier

.Lattn_tb18:
	ds_read_b128 v[216:219], v187 offset:0
	ds_read_b128 v[220:223], v187 offset:4096
	ds_read_b128 v[224:227], v187 offset:8192
	ds_read_b128 v[228:231], v187 offset:12288
	ds_read_b128 v[208:211], v188 offset:0
	ds_read_b128 v[212:215], v188 offset:4096
	v_max3_f32 v254, v64, v65, v66
	s_add_i32 s2, s42, 4
	v_max3_f32 v255, v80, v81, v82
	s_and_b32 s2, s2, 31
	v_max3_f32 v254, v254, v67, v68
	s_mul_i32 s2, s2, 0x44000
	v_max3_f32 v255, v255, v83, v84
	s_add_i32 m0, s5, 0
	v_max3_f32 v254, v254, v69, v70
	s_add_u32 s40, s26, s2
	v_max3_f32 v255, v255, v85, v86
	s_addc_u32 s41, s27, 0
	v_max3_f32 v254, v254, v71, v72
	global_load_lds_dwordx4 v170, s[40:41]
	v_max3_f32 v255, v255, v87, v88
	s_add_i32 m0, s5, 8192
	v_max3_f32 v254, v254, v73, v74
	s_add_u32 s40, s40, 0x80
	v_max3_f32 v255, v255, v89, v90
	s_addc_u32 s41, s41, 0
	v_max3_f32 v254, v254, v75, v76
	global_load_lds_dwordx4 v170, s[40:41]
	v_max3_f32 v255, v255, v91, v92
	s_add_i32 s2, s42, 2
	v_max3_f32 v254, v254, v77, v78
	s_and_b32 s2, s2, 31
	v_max3_f32 v255, v255, v93, v94
	s_lshl_b32 s2, s2, 7
	v_max3_f32 v254, v254, v79, v95
	s_add_i32 m0, s5, 98304
	v_max_f32_e32 v254, v254, v255
	s_add_u32 s44, s10, s2
	s_addc_u32 s45, s11, 0
	global_load_lds_dwordx4 v172, s[44:45]
	s_add_i32 m0, s5, 106496
	s_add_u32 s44, s44, 0x204000
	s_addc_u32 s45, s45, 0
	global_load_lds_dwordx4 v172, s[44:45]
	v_mov_b32_e32 v180, 0xc2800000
	v_cmp_lt_f32_e32 vcc, 0x4138aa3b, v254
	v_cmp_gt_f32_e64 s[40:41], v180, v254
	s_nop 4
	s_or_b64 vcc, vcc, s[40:41]
	s_nop 0
.Lattn_sp_t0:
	v_mov_b32_e32 v175, v243
	v_mov_b32_e32 v255, v254
	s_nop 1
	v_permlane32_swap_b32_e32 v254, v255
	v_max_f32_e32 v254, v254, v255
	v_add_f32_e32 v180, 0x4138aa3b, v175
	v_cmp_gt_f32_e32 vcc, v254, v180
	s_nop 1
	v_cndmask_b32_e32 v180, v175, v254, vcc
	v_sub_f32_e32 v255, v175, v180
	v_exp_f32_e32 v174, v255
	v_mov_b32_e32 v175, v180
	v_sub_f32_e32 v64, v64, v175
	v_sub_f32_e32 v65, v65, v175
	v_sub_f32_e32 v66, v66, v175
	v_sub_f32_e32 v67, v67, v175
	v_sub_f32_e32 v68, v68, v175
	v_sub_f32_e32 v69, v69, v175
	v_sub_f32_e32 v70, v70, v175
	v_sub_f32_e32 v71, v71, v175
	v_exp_f32_e32 v64, v64
	v_exp_f32_e32 v65, v65
	v_exp_f32_e32 v66, v66
	v_exp_f32_e32 v67, v67
	v_exp_f32_e32 v68, v68
	v_exp_f32_e32 v69, v69
	v_exp_f32_e32 v70, v70
	v_exp_f32_e32 v71, v71
	v_add_f32_e32 v190, v64, v65
	v_add_f32_e32 v191, v66, v67
	v_add_f32_e32 v190, v190, v68
	v_add_f32_e32 v191, v191, v69
	v_add_f32_e32 v190, v190, v70
	v_add_f32_e32 v191, v191, v71
	v_cvt_pk_bf16_f32 v144, v64, v65
	v_cvt_pk_bf16_f32 v145, v66, v67
	v_cvt_pk_bf16_f32 v146, v68, v69
	v_cvt_pk_bf16_f32 v147, v70, v71
	v_sub_f32_e32 v72, v72, v175
	v_sub_f32_e32 v73, v73, v175
	v_sub_f32_e32 v74, v74, v175
	v_sub_f32_e32 v75, v75, v175
	v_sub_f32_e32 v76, v76, v175
	v_sub_f32_e32 v77, v77, v175
	v_sub_f32_e32 v78, v78, v175
	v_sub_f32_e32 v79, v79, v175
	v_exp_f32_e32 v72, v72
	v_exp_f32_e32 v73, v73
	v_exp_f32_e32 v74, v74
	v_exp_f32_e32 v75, v75
	v_exp_f32_e32 v76, v76
	v_exp_f32_e32 v77, v77
	v_exp_f32_e32 v78, v78
	v_exp_f32_e32 v79, v79
	v_add_f32_e32 v190, v190, v72
	v_add_f32_e32 v191, v191, v73
	v_add_f32_e32 v190, v190, v74
	v_add_f32_e32 v191, v191, v75
	v_add_f32_e32 v190, v190, v76
	v_add_f32_e32 v191, v191, v77
	v_add_f32_e32 v190, v190, v78
	v_add_f32_e32 v191, v191, v79
	v_cvt_pk_bf16_f32 v148, v72, v73
	v_cvt_pk_bf16_f32 v149, v74, v75
	v_cvt_pk_bf16_f32 v150, v76, v77
	v_cvt_pk_bf16_f32 v151, v78, v79
	v_sub_f32_e32 v80, v80, v175
	v_sub_f32_e32 v81, v81, v175
	v_sub_f32_e32 v82, v82, v175
	v_sub_f32_e32 v83, v83, v175
	v_sub_f32_e32 v84, v84, v175
	v_sub_f32_e32 v85, v85, v175
	v_sub_f32_e32 v86, v86, v175
	v_sub_f32_e32 v87, v87, v175
	v_exp_f32_e32 v80, v80
	v_exp_f32_e32 v81, v81
	v_exp_f32_e32 v82, v82
	v_exp_f32_e32 v83, v83
	v_exp_f32_e32 v84, v84
	v_exp_f32_e32 v85, v85
	v_exp_f32_e32 v86, v86
	v_exp_f32_e32 v87, v87
	v_add_f32_e32 v190, v190, v80
	v_add_f32_e32 v191, v191, v81
	v_add_f32_e32 v190, v190, v82
	v_add_f32_e32 v191, v191, v83
	v_add_f32_e32 v190, v190, v84
	v_add_f32_e32 v191, v191, v85
	v_add_f32_e32 v190, v190, v86
	v_add_f32_e32 v191, v191, v87
	v_cvt_pk_bf16_f32 v152, v80, v81
	v_cvt_pk_bf16_f32 v153, v82, v83
	v_cvt_pk_bf16_f32 v154, v84, v85
	v_cvt_pk_bf16_f32 v155, v86, v87
	v_sub_f32_e32 v88, v88, v175
	v_sub_f32_e32 v89, v89, v175
	v_sub_f32_e32 v90, v90, v175
	v_sub_f32_e32 v91, v91, v175
	v_sub_f32_e32 v92, v92, v175
	v_sub_f32_e32 v93, v93, v175
	v_sub_f32_e32 v94, v94, v175
	v_sub_f32_e32 v95, v95, v175
	v_exp_f32_e32 v88, v88
	v_exp_f32_e32 v89, v89
	v_exp_f32_e32 v90, v90
	v_exp_f32_e32 v91, v91
	v_exp_f32_e32 v92, v92
	v_exp_f32_e32 v93, v93
	v_exp_f32_e32 v94, v94
	v_exp_f32_e32 v95, v95
	v_add_f32_e32 v190, v190, v88
	v_add_f32_e32 v191, v191, v89
	v_add_f32_e32 v190, v190, v90
	v_add_f32_e32 v191, v191, v91
	v_add_f32_e32 v190, v190, v92
	v_add_f32_e32 v191, v191, v93
	v_add_f32_e32 v190, v190, v94
	v_add_f32_e32 v191, v191, v95
	v_cvt_pk_bf16_f32 v156, v88, v89
	v_cvt_pk_bf16_f32 v157, v90, v91
	v_cvt_pk_bf16_f32 v158, v92, v93
	v_cvt_pk_bf16_f32 v159, v94, v95
	v_add_f32_e32 v190, v190, v191
	v_fma_f32 v167, v167, v174, v190
	s_cbranch_vccz .Lattn_noresc_t0
	s_nop 7
	s_nop 7
	v_pk_mul_f32 v[0:1], v[0:1], v[174:175] op_sel_hi:[1,0]
	v_pk_mul_f32 v[2:3], v[2:3], v[174:175] op_sel_hi:[1,0]
	v_pk_mul_f32 v[4:5], v[4:5], v[174:175] op_sel_hi:[1,0]
	v_pk_mul_f32 v[6:7], v[6:7], v[174:175] op_sel_hi:[1,0]
	v_pk_mul_f32 v[8:9], v[8:9], v[174:175] op_sel_hi:[1,0]
	v_pk_mul_f32 v[10:11], v[10:11], v[174:175] op_sel_hi:[1,0]
	v_pk_mul_f32 v[12:13], v[12:13], v[174:175] op_sel_hi:[1,0]
	v_pk_mul_f32 v[14:15], v[14:15], v[174:175] op_sel_hi:[1,0]
	v_pk_mul_f32 v[16:17], v[16:17], v[174:175] op_sel_hi:[1,0]
	v_pk_mul_f32 v[18:19], v[18:19], v[174:175] op_sel_hi:[1,0]
	v_pk_mul_f32 v[20:21], v[20:21], v[174:175] op_sel_hi:[1,0]
	v_pk_mul_f32 v[22:23], v[22:23], v[174:175] op_sel_hi:[1,0]
	v_pk_mul_f32 v[24:25], v[24:25], v[174:175] op_sel_hi:[1,0]
	v_pk_mul_f32 v[26:27], v[26:27], v[174:175] op_sel_hi:[1,0]
	v_pk_mul_f32 v[28:29], v[28:29], v[174:175] op_sel_hi:[1,0]
	v_pk_mul_f32 v[30:31], v[30:31], v[174:175] op_sel_hi:[1,0]
	v_pk_mul_f32 v[32:33], v[32:33], v[174:175] op_sel_hi:[1,0]
	v_pk_mul_f32 v[34:35], v[34:35], v[174:175] op_sel_hi:[1,0]
	v_pk_mul_f32 v[36:37], v[36:37], v[174:175] op_sel_hi:[1,0]
	v_pk_mul_f32 v[38:39], v[38:39], v[174:175] op_sel_hi:[1,0]
	v_pk_mul_f32 v[40:41], v[40:41], v[174:175] op_sel_hi:[1,0]
	v_pk_mul_f32 v[42:43], v[42:43], v[174:175] op_sel_hi:[1,0]
	v_pk_mul_f32 v[44:45], v[44:45], v[174:175] op_sel_hi:[1,0]
	v_pk_mul_f32 v[46:47], v[46:47], v[174:175] op_sel_hi:[1,0]
	v_pk_mul_f32 v[48:49], v[48:49], v[174:175] op_sel_hi:[1,0]
	v_pk_mul_f32 v[50:51], v[50:51], v[174:175] op_sel_hi:[1,0]
	v_pk_mul_f32 v[52:53], v[52:53], v[174:175] op_sel_hi:[1,0]
	v_pk_mul_f32 v[54:55], v[54:55], v[174:175] op_sel_hi:[1,0]
	v_pk_mul_f32 v[56:57], v[56:57], v[174:175] op_sel_hi:[1,0]
	v_pk_mul_f32 v[58:59], v[58:59], v[174:175] op_sel_hi:[1,0]
	v_pk_mul_f32 v[60:61], v[60:61], v[174:175] op_sel_hi:[1,0]
	v_pk_mul_f32 v[62:63], v[62:63], v[174:175] op_sel_hi:[1,0]
	s_nop 1

.Lattn_loop_s:
.Lattn_top_L0:
	s_cmp_lg_u32 s14, 0
	s_cbranch_scc1 .Lattn_tb19
	s_waitcnt vmcnt(4)
	s_barrier

.Lattn_tb20:
	ds_read_b128 v[216:219], v187 offset:16384
	ds_read_b128 v[220:223], v187 offset:20480
	ds_read_b128 v[224:227], v187 offset:24576
	ds_read_b128 v[228:231], v187 offset:28672
	ds_read_b128 v[208:211], v188 offset:16384
	ds_read_b128 v[212:215], v188 offset:20480
	v_max3_f32 v254, v96, v97, v98
	s_add_i32 s2, s42, 4
	v_max3_f32 v255, v112, v113, v114
	s_and_b32 s2, s2, 31
	v_max3_f32 v254, v254, v99, v100
	s_mul_i32 s2, s2, 0x44000
	v_max3_f32 v255, v255, v115, v116
	s_add_i32 m0, s5, 16384
	v_max3_f32 v254, v254, v101, v102
	s_add_u32 s40, s26, s2
	v_max3_f32 v255, v255, v117, v118
	s_addc_u32 s41, s27, 0
	v_max3_f32 v254, v254, v103, v104
	global_load_lds_dwordx4 v170, s[40:41]
	v_max3_f32 v255, v255, v119, v120
	s_add_i32 m0, s5, 24576
	v_max3_f32 v254, v254, v105, v106
	s_add_u32 s40, s40, 0x80
	v_max3_f32 v255, v255, v121, v122
	s_addc_u32 s41, s41, 0
	v_max3_f32 v254, v254, v107, v108
	global_load_lds_dwordx4 v170, s[40:41]
	v_max3_f32 v255, v255, v123, v124
	s_add_i32 s2, s42, 2
	v_max3_f32 v254, v254, v109, v110
	s_and_b32 s2, s2, 31
	v_max3_f32 v255, v255, v125, v126
	s_lshl_b32 s2, s2, 7
	v_max3_f32 v254, v254, v111, v127
	s_add_i32 m0, s5, 114688
	v_max_f32_e32 v254, v254, v255
	s_add_u32 s44, s10, s2
	s_addc_u32 s45, s11, 0
	global_load_lds_dwordx4 v172, s[44:45]
	s_add_i32 m0, s5, 122880
	s_add_u32 s44, s44, 0x204000
	s_addc_u32 s45, s45, 0
	global_load_lds_dwordx4 v172, s[44:45]
	v_mov_b32_e32 v255, v254
	s_nop 1
	v_permlane32_swap_b32_e32 v254, v255
	v_max_f32_e32 v254, v254, v255
	v_add_f32_e32 v180, 0x4138aa3b, v175
	v_cmp_gt_f32_e32 vcc, v254, v180
	s_nop 1
	v_cndmask_b32_e32 v180, v175, v254, vcc
	v_sub_f32_e32 v255, v175, v180
	v_exp_f32_e32 v174, v255
	v_mov_b32_e32 v175, v180
	v_sub_f32_e32 v96, v96, v175
	v_sub_f32_e32 v97, v97, v175
	v_sub_f32_e32 v98, v98, v175
	v_sub_f32_e32 v99, v99, v175
	v_sub_f32_e32 v100, v100, v175
	v_sub_f32_e32 v101, v101, v175
	v_sub_f32_e32 v102, v102, v175
	v_sub_f32_e32 v103, v103, v175
	v_exp_f32_e32 v96, v96
	v_exp_f32_e32 v97, v97
	v_exp_f32_e32 v98, v98
	v_exp_f32_e32 v99, v99
	v_exp_f32_e32 v100, v100
	v_exp_f32_e32 v101, v101
	v_exp_f32_e32 v102, v102
	v_exp_f32_e32 v103, v103
	v_add_f32_e32 v190, v96, v97
	v_add_f32_e32 v191, v98, v99
	v_add_f32_e32 v190, v190, v100
	v_add_f32_e32 v191, v191, v101
	v_add_f32_e32 v190, v190, v102
	v_add_f32_e32 v191, v191, v103
	v_cvt_pk_bf16_f32 v144, v96, v97
	v_cvt_pk_bf16_f32 v145, v98, v99
	v_cvt_pk_bf16_f32 v146, v100, v101
	v_cvt_pk_bf16_f32 v147, v102, v103
	v_sub_f32_e32 v104, v104, v175
	v_sub_f32_e32 v105, v105, v175
	v_sub_f32_e32 v106, v106, v175
	v_sub_f32_e32 v107, v107, v175
	v_sub_f32_e32 v108, v108, v175
	v_sub_f32_e32 v109, v109, v175
	v_sub_f32_e32 v110, v110, v175
	v_sub_f32_e32 v111, v111, v175
	v_exp_f32_e32 v104, v104
	v_exp_f32_e32 v105, v105
	v_exp_f32_e32 v106, v106
	v_exp_f32_e32 v107, v107
	v_exp_f32_e32 v108, v108
	v_exp_f32_e32 v109, v109
	v_exp_f32_e32 v110, v110
	v_exp_f32_e32 v111, v111
	v_add_f32_e32 v190, v190, v104
	v_add_f32_e32 v191, v191, v105
	v_add_f32_e32 v190, v190, v106
	v_add_f32_e32 v191, v191, v107
	v_add_f32_e32 v190, v190, v108
	v_add_f32_e32 v191, v191, v109
	v_add_f32_e32 v190, v190, v110
	v_add_f32_e32 v191, v191, v111
	v_cvt_pk_bf16_f32 v148, v104, v105
	v_cvt_pk_bf16_f32 v149, v106, v107
	v_cvt_pk_bf16_f32 v150, v108, v109
	v_cvt_pk_bf16_f32 v151, v110, v111
	v_sub_f32_e32 v112, v112, v175
	v_sub_f32_e32 v113, v113, v175
	v_sub_f32_e32 v114, v114, v175
	v_sub_f32_e32 v115, v115, v175
	v_sub_f32_e32 v116, v116, v175
	v_sub_f32_e32 v117, v117, v175
	v_sub_f32_e32 v118, v118, v175
	v_sub_f32_e32 v119, v119, v175
	v_exp_f32_e32 v112, v112
	v_exp_f32_e32 v113, v113
	v_exp_f32_e32 v114, v114
	v_exp_f32_e32 v115, v115
	v_exp_f32_e32 v116, v116
	v_exp_f32_e32 v117, v117
	v_exp_f32_e32 v118, v118
	v_exp_f32_e32 v119, v119
	v_add_f32_e32 v190, v190, v112
	v_add_f32_e32 v191, v191, v113
	v_add_f32_e32 v190, v190, v114
	v_add_f32_e32 v191, v191, v115
	v_add_f32_e32 v190, v190, v116
	v_add_f32_e32 v191, v191, v117
	v_add_f32_e32 v190, v190, v118
	v_add_f32_e32 v191, v191, v119
	v_cvt_pk_bf16_f32 v152, v112, v113
	v_cvt_pk_bf16_f32 v153, v114, v115
	v_cvt_pk_bf16_f32 v154, v116, v117
	v_cvt_pk_bf16_f32 v155, v118, v119
	v_sub_f32_e32 v120, v120, v175
	v_sub_f32_e32 v121, v121, v175
	v_sub_f32_e32 v122, v122, v175
	v_sub_f32_e32 v123, v123, v175
	v_sub_f32_e32 v124, v124, v175
	v_sub_f32_e32 v125, v125, v175
	v_sub_f32_e32 v126, v126, v175
	v_sub_f32_e32 v127, v127, v175
	v_exp_f32_e32 v120, v120
	v_exp_f32_e32 v121, v121
	v_exp_f32_e32 v122, v122
	v_exp_f32_e32 v123, v123
	v_exp_f32_e32 v124, v124
	v_exp_f32_e32 v125, v125
	v_exp_f32_e32 v126, v126
	v_exp_f32_e32 v127, v127
	v_add_f32_e32 v190, v190, v120
	v_add_f32_e32 v191, v191, v121
	v_add_f32_e32 v190, v190, v122
	v_add_f32_e32 v191, v191, v123
	v_add_f32_e32 v190, v190, v124
	v_add_f32_e32 v191, v191, v125
	v_add_f32_e32 v190, v190, v126
	v_add_f32_e32 v191, v191, v127
	v_cvt_pk_bf16_f32 v156, v120, v121
	v_cvt_pk_bf16_f32 v157, v122, v123
	v_cvt_pk_bf16_f32 v158, v124, v125
	v_cvt_pk_bf16_f32 v159, v126, v127
	v_add_f32_e32 v190, v190, v191
	v_fma_f32 v167, v167, v174, v190
	s_cbranch_vccz .Lattn_noresc_L0
	s_nop 7
	s_nop 7
	v_pk_mul_f32 v[0:1], v[0:1], v[174:175] op_sel_hi:[1,0]
	v_pk_mul_f32 v[2:3], v[2:3], v[174:175] op_sel_hi:[1,0]
	v_pk_mul_f32 v[4:5], v[4:5], v[174:175] op_sel_hi:[1,0]
	v_pk_mul_f32 v[6:7], v[6:7], v[174:175] op_sel_hi:[1,0]
	v_pk_mul_f32 v[8:9], v[8:9], v[174:175] op_sel_hi:[1,0]
	v_pk_mul_f32 v[10:11], v[10:11], v[174:175] op_sel_hi:[1,0]
	v_pk_mul_f32 v[12:13], v[12:13], v[174:175] op_sel_hi:[1,0]
	v_pk_mul_f32 v[14:15], v[14:15], v[174:175] op_sel_hi:[1,0]
	v_pk_mul_f32 v[16:17], v[16:17], v[174:175] op_sel_hi:[1,0]
	v_pk_mul_f32 v[18:19], v[18:19], v[174:175] op_sel_hi:[1,0]
	v_pk_mul_f32 v[20:21], v[20:21], v[174:175] op_sel_hi:[1,0]
	v_pk_mul_f32 v[22:23], v[22:23], v[174:175] op_sel_hi:[1,0]
	v_pk_mul_f32 v[24:25], v[24:25], v[174:175] op_sel_hi:[1,0]
	v_pk_mul_f32 v[26:27], v[26:27], v[174:175] op_sel_hi:[1,0]
	v_pk_mul_f32 v[28:29], v[28:29], v[174:175] op_sel_hi:[1,0]
	v_pk_mul_f32 v[30:31], v[30:31], v[174:175] op_sel_hi:[1,0]
	v_pk_mul_f32 v[32:33], v[32:33], v[174:175] op_sel_hi:[1,0]
	v_pk_mul_f32 v[34:35], v[34:35], v[174:175] op_sel_hi:[1,0]
	v_pk_mul_f32 v[36:37], v[36:37], v[174:175] op_sel_hi:[1,0]
	v_pk_mul_f32 v[38:39], v[38:39], v[174:175] op_sel_hi:[1,0]
	v_pk_mul_f32 v[40:41], v[40:41], v[174:175] op_sel_hi:[1,0]
	v_pk_mul_f32 v[42:43], v[42:43], v[174:175] op_sel_hi:[1,0]
	v_pk_mul_f32 v[44:45], v[44:45], v[174:175] op_sel_hi:[1,0]
	v_pk_mul_f32 v[46:47], v[46:47], v[174:175] op_sel_hi:[1,0]
	v_pk_mul_f32 v[48:49], v[48:49], v[174:175] op_sel_hi:[1,0]
	v_pk_mul_f32 v[50:51], v[50:51], v[174:175] op_sel_hi:[1,0]
	v_pk_mul_f32 v[52:53], v[52:53], v[174:175] op_sel_hi:[1,0]
	v_pk_mul_f32 v[54:55], v[54:55], v[174:175] op_sel_hi:[1,0]
	v_pk_mul_f32 v[56:57], v[56:57], v[174:175] op_sel_hi:[1,0]
	v_pk_mul_f32 v[58:59], v[58:59], v[174:175] op_sel_hi:[1,0]
	v_pk_mul_f32 v[60:61], v[60:61], v[174:175] op_sel_hi:[1,0]
	v_pk_mul_f32 v[62:63], v[62:63], v[174:175] op_sel_hi:[1,0]
	s_nop 1

.Lattn_tb22:
	ds_read_b128 v[216:219], v187 offset:32768
	ds_read_b128 v[220:223], v187 offset:36864
	ds_read_b128 v[224:227], v187 offset:40960
	ds_read_b128 v[228:231], v187 offset:45056
	ds_read_b128 v[208:211], v188 offset:32768
	ds_read_b128 v[212:215], v188 offset:36864
	v_max3_f32 v254, v64, v65, v66
	s_add_i32 s2, s42, 5
	v_max3_f32 v255, v80, v81, v82
	s_and_b32 s2, s2, 31
	v_max3_f32 v254, v254, v67, v68
	s_mul_i32 s2, s2, 0x44000
	v_max3_f32 v255, v255, v83, v84
	s_add_i32 m0, s5, 32768
	v_max3_f32 v254, v254, v69, v70
	s_add_u32 s40, s26, s2
	v_max3_f32 v255, v255, v85, v86
	s_addc_u32 s41, s27, 0
	v_max3_f32 v254, v254, v71, v72
	global_load_lds_dwordx4 v170, s[40:41]
	v_max3_f32 v255, v255, v87, v88
	s_add_i32 m0, s5, 40960
	v_max3_f32 v254, v254, v73, v74
	s_add_u32 s40, s40, 0x80
	v_max3_f32 v255, v255, v89, v90
	s_addc_u32 s41, s41, 0
	v_max3_f32 v254, v254, v75, v76
	global_load_lds_dwordx4 v170, s[40:41]
	v_max3_f32 v255, v255, v91, v92
	s_add_i32 s2, s42, 3
	v_max3_f32 v254, v254, v77, v78
	s_and_b32 s2, s2, 31
	v_max3_f32 v255, v255, v93, v94
	s_lshl_b32 s2, s2, 7
	v_max3_f32 v254, v254, v79, v95
	s_add_i32 m0, s5, 65536
	v_max_f32_e32 v254, v254, v255
	s_add_u32 s44, s10, s2
	s_addc_u32 s45, s11, 0
	global_load_lds_dwordx4 v172, s[44:45]
	s_add_i32 m0, s5, 73728
	s_add_u32 s44, s44, 0x204000
	s_addc_u32 s45, s45, 0
	global_load_lds_dwordx4 v172, s[44:45]
	v_mov_b32_e32 v255, v254
	s_nop 1
	v_permlane32_swap_b32_e32 v254, v255
	v_max_f32_e32 v254, v254, v255
	v_add_f32_e32 v180, 0x4138aa3b, v175
	v_cmp_gt_f32_e32 vcc, v254, v180
	s_nop 1
	v_cndmask_b32_e32 v180, v175, v254, vcc
	v_sub_f32_e32 v255, v175, v180
	v_exp_f32_e32 v174, v255
	v_mov_b32_e32 v175, v180
	v_sub_f32_e32 v64, v64, v175
	v_sub_f32_e32 v65, v65, v175
	v_sub_f32_e32 v66, v66, v175
	v_sub_f32_e32 v67, v67, v175
	v_sub_f32_e32 v68, v68, v175
	v_sub_f32_e32 v69, v69, v175
	v_sub_f32_e32 v70, v70, v175
	v_sub_f32_e32 v71, v71, v175
	v_exp_f32_e32 v64, v64
	v_exp_f32_e32 v65, v65
	v_exp_f32_e32 v66, v66
	v_exp_f32_e32 v67, v67
	v_exp_f32_e32 v68, v68
	v_exp_f32_e32 v69, v69
	v_exp_f32_e32 v70, v70
	v_exp_f32_e32 v71, v71
	v_add_f32_e32 v190, v64, v65
	v_add_f32_e32 v191, v66, v67
	v_add_f32_e32 v190, v190, v68
	v_add_f32_e32 v191, v191, v69
	v_add_f32_e32 v190, v190, v70
	v_add_f32_e32 v191, v191, v71
	v_cvt_pk_bf16_f32 v144, v64, v65
	v_cvt_pk_bf16_f32 v145, v66, v67
	v_cvt_pk_bf16_f32 v146, v68, v69
	v_cvt_pk_bf16_f32 v147, v70, v71
	v_sub_f32_e32 v72, v72, v175
	v_sub_f32_e32 v73, v73, v175
	v_sub_f32_e32 v74, v74, v175
	v_sub_f32_e32 v75, v75, v175
	v_sub_f32_e32 v76, v76, v175
	v_sub_f32_e32 v77, v77, v175
	v_sub_f32_e32 v78, v78, v175
	v_sub_f32_e32 v79, v79, v175
	v_exp_f32_e32 v72, v72
	v_exp_f32_e32 v73, v73
	v_exp_f32_e32 v74, v74
	v_exp_f32_e32 v75, v75
	v_exp_f32_e32 v76, v76
	v_exp_f32_e32 v77, v77
	v_exp_f32_e32 v78, v78
	v_exp_f32_e32 v79, v79
	v_add_f32_e32 v190, v190, v72
	v_add_f32_e32 v191, v191, v73
	v_add_f32_e32 v190, v190, v74
	v_add_f32_e32 v191, v191, v75
	v_add_f32_e32 v190, v190, v76
	v_add_f32_e32 v191, v191, v77
	v_add_f32_e32 v190, v190, v78
	v_add_f32_e32 v191, v191, v79
	v_cvt_pk_bf16_f32 v148, v72, v73
	v_cvt_pk_bf16_f32 v149, v74, v75
	v_cvt_pk_bf16_f32 v150, v76, v77
	v_cvt_pk_bf16_f32 v151, v78, v79
	v_sub_f32_e32 v80, v80, v175
	v_sub_f32_e32 v81, v81, v175
	v_sub_f32_e32 v82, v82, v175
	v_sub_f32_e32 v83, v83, v175
	v_sub_f32_e32 v84, v84, v175
	v_sub_f32_e32 v85, v85, v175
	v_sub_f32_e32 v86, v86, v175
	v_sub_f32_e32 v87, v87, v175
	v_exp_f32_e32 v80, v80
	v_exp_f32_e32 v81, v81
	v_exp_f32_e32 v82, v82
	v_exp_f32_e32 v83, v83
	v_exp_f32_e32 v84, v84
	v_exp_f32_e32 v85, v85
	v_exp_f32_e32 v86, v86
	v_exp_f32_e32 v87, v87
	v_add_f32_e32 v190, v190, v80
	v_add_f32_e32 v191, v191, v81
	v_add_f32_e32 v190, v190, v82
	v_add_f32_e32 v191, v191, v83
	v_add_f32_e32 v190, v190, v84
	v_add_f32_e32 v191, v191, v85
	v_add_f32_e32 v190, v190, v86
	v_add_f32_e32 v191, v191, v87
	v_cvt_pk_bf16_f32 v152, v80, v81
	v_cvt_pk_bf16_f32 v153, v82, v83
	v_cvt_pk_bf16_f32 v154, v84, v85
	v_cvt_pk_bf16_f32 v155, v86, v87
	v_sub_f32_e32 v88, v88, v175
	v_sub_f32_e32 v89, v89, v175
	v_sub_f32_e32 v90, v90, v175
	v_sub_f32_e32 v91, v91, v175
	v_sub_f32_e32 v92, v92, v175
	v_sub_f32_e32 v93, v93, v175
	v_sub_f32_e32 v94, v94, v175
	v_sub_f32_e32 v95, v95, v175
	v_exp_f32_e32 v88, v88
	v_exp_f32_e32 v89, v89
	v_exp_f32_e32 v90, v90
	v_exp_f32_e32 v91, v91
	v_exp_f32_e32 v92, v92
	v_exp_f32_e32 v93, v93
	v_exp_f32_e32 v94, v94
	v_exp_f32_e32 v95, v95
	v_add_f32_e32 v190, v190, v88
	v_add_f32_e32 v191, v191, v89
	v_add_f32_e32 v190, v190, v90
	v_add_f32_e32 v191, v191, v91
	v_add_f32_e32 v190, v190, v92
	v_add_f32_e32 v191, v191, v93
	v_add_f32_e32 v190, v190, v94
	v_add_f32_e32 v191, v191, v95
	v_cvt_pk_bf16_f32 v156, v88, v89
	v_cvt_pk_bf16_f32 v157, v90, v91
	v_cvt_pk_bf16_f32 v158, v92, v93
	v_cvt_pk_bf16_f32 v159, v94, v95
	v_add_f32_e32 v190, v190, v191
	v_fma_f32 v167, v167, v174, v190
	s_cbranch_vccz .Lattn_noresc_L1
	s_nop 7
	s_nop 7
	v_pk_mul_f32 v[0:1], v[0:1], v[174:175] op_sel_hi:[1,0]
	v_pk_mul_f32 v[2:3], v[2:3], v[174:175] op_sel_hi:[1,0]
	v_pk_mul_f32 v[4:5], v[4:5], v[174:175] op_sel_hi:[1,0]
	v_pk_mul_f32 v[6:7], v[6:7], v[174:175] op_sel_hi:[1,0]
	v_pk_mul_f32 v[8:9], v[8:9], v[174:175] op_sel_hi:[1,0]
	v_pk_mul_f32 v[10:11], v[10:11], v[174:175] op_sel_hi:[1,0]
	v_pk_mul_f32 v[12:13], v[12:13], v[174:175] op_sel_hi:[1,0]
	v_pk_mul_f32 v[14:15], v[14:15], v[174:175] op_sel_hi:[1,0]
	v_pk_mul_f32 v[16:17], v[16:17], v[174:175] op_sel_hi:[1,0]
	v_pk_mul_f32 v[18:19], v[18:19], v[174:175] op_sel_hi:[1,0]
	v_pk_mul_f32 v[20:21], v[20:21], v[174:175] op_sel_hi:[1,0]
	v_pk_mul_f32 v[22:23], v[22:23], v[174:175] op_sel_hi:[1,0]
	v_pk_mul_f32 v[24:25], v[24:25], v[174:175] op_sel_hi:[1,0]
	v_pk_mul_f32 v[26:27], v[26:27], v[174:175] op_sel_hi:[1,0]
	v_pk_mul_f32 v[28:29], v[28:29], v[174:175] op_sel_hi:[1,0]
	v_pk_mul_f32 v[30:31], v[30:31], v[174:175] op_sel_hi:[1,0]
	v_pk_mul_f32 v[32:33], v[32:33], v[174:175] op_sel_hi:[1,0]
	v_pk_mul_f32 v[34:35], v[34:35], v[174:175] op_sel_hi:[1,0]
	v_pk_mul_f32 v[36:37], v[36:37], v[174:175] op_sel_hi:[1,0]
	v_pk_mul_f32 v[38:39], v[38:39], v[174:175] op_sel_hi:[1,0]
	v_pk_mul_f32 v[40:41], v[40:41], v[174:175] op_sel_hi:[1,0]
	v_pk_mul_f32 v[42:43], v[42:43], v[174:175] op_sel_hi:[1,0]
	v_pk_mul_f32 v[44:45], v[44:45], v[174:175] op_sel_hi:[1,0]
	v_pk_mul_f32 v[46:47], v[46:47], v[174:175] op_sel_hi:[1,0]
	v_pk_mul_f32 v[48:49], v[48:49], v[174:175] op_sel_hi:[1,0]
	v_pk_mul_f32 v[50:51], v[50:51], v[174:175] op_sel_hi:[1,0]
	v_pk_mul_f32 v[52:53], v[52:53], v[174:175] op_sel_hi:[1,0]
	v_pk_mul_f32 v[54:55], v[54:55], v[174:175] op_sel_hi:[1,0]
	v_pk_mul_f32 v[56:57], v[56:57], v[174:175] op_sel_hi:[1,0]
	v_pk_mul_f32 v[58:59], v[58:59], v[174:175] op_sel_hi:[1,0]
	v_pk_mul_f32 v[60:61], v[60:61], v[174:175] op_sel_hi:[1,0]
	v_pk_mul_f32 v[62:63], v[62:63], v[174:175] op_sel_hi:[1,0]
	s_nop 1

.Lattn_tb24:
	ds_read_b128 v[216:219], v187 offset:49152
	ds_read_b128 v[220:223], v187 offset:53248
	ds_read_b128 v[224:227], v187 offset:57344
	ds_read_b128 v[228:231], v187 offset:61440
	ds_read_b128 v[208:211], v188 offset:49152
	ds_read_b128 v[212:215], v188 offset:53248
	v_max3_f32 v254, v96, v97, v98
	s_add_i32 s2, s42, 6
	v_max3_f32 v255, v112, v113, v114
	s_and_b32 s2, s2, 31
	v_max3_f32 v254, v254, v99, v100
	s_mul_i32 s2, s2, 0x44000
	v_max3_f32 v255, v255, v115, v116
	s_add_i32 m0, s5, 49152
	v_max3_f32 v254, v254, v101, v102
	s_add_u32 s40, s26, s2
	v_max3_f32 v255, v255, v117, v118
	s_addc_u32 s41, s27, 0
	v_max3_f32 v254, v254, v103, v104
	global_load_lds_dwordx4 v170, s[40:41]
	v_max3_f32 v255, v255, v119, v120
	s_add_i32 m0, s5, 57344
	v_max3_f32 v254, v254, v105, v106
	s_add_u32 s40, s40, 0x80
	v_max3_f32 v255, v255, v121, v122
	s_addc_u32 s41, s41, 0
	v_max3_f32 v254, v254, v107, v108
	global_load_lds_dwordx4 v170, s[40:41]
	v_max3_f32 v255, v255, v123, v124
	s_add_i32 s2, s42, 4
	v_max3_f32 v254, v254, v109, v110
	s_and_b32 s2, s2, 31
	v_max3_f32 v255, v255, v125, v126
	s_lshl_b32 s2, s2, 7
	v_max3_f32 v254, v254, v111, v127
	s_add_i32 m0, s5, 81920
	v_max_f32_e32 v254, v254, v255
	s_add_u32 s44, s10, s2
	s_addc_u32 s45, s11, 0
	global_load_lds_dwordx4 v172, s[44:45]
	s_add_i32 m0, s5, 90112
	s_add_u32 s44, s44, 0x204000
	s_addc_u32 s45, s45, 0
	global_load_lds_dwordx4 v172, s[44:45]
	v_mov_b32_e32 v255, v254
	s_nop 1
	v_permlane32_swap_b32_e32 v254, v255
	v_max_f32_e32 v254, v254, v255
	v_add_f32_e32 v180, 0x4138aa3b, v175
	v_cmp_gt_f32_e32 vcc, v254, v180
	s_nop 1
	v_cndmask_b32_e32 v180, v175, v254, vcc
	v_sub_f32_e32 v255, v175, v180
	v_exp_f32_e32 v174, v255
	v_mov_b32_e32 v175, v180
	v_sub_f32_e32 v96, v96, v175
	v_sub_f32_e32 v97, v97, v175
	v_sub_f32_e32 v98, v98, v175
	v_sub_f32_e32 v99, v99, v175
	v_sub_f32_e32 v100, v100, v175
	v_sub_f32_e32 v101, v101, v175
	v_sub_f32_e32 v102, v102, v175
	v_sub_f32_e32 v103, v103, v175
	v_exp_f32_e32 v96, v96
	v_exp_f32_e32 v97, v97
	v_exp_f32_e32 v98, v98
	v_exp_f32_e32 v99, v99
	v_exp_f32_e32 v100, v100
	v_exp_f32_e32 v101, v101
	v_exp_f32_e32 v102, v102
	v_exp_f32_e32 v103, v103
	v_add_f32_e32 v190, v96, v97
	v_add_f32_e32 v191, v98, v99
	v_add_f32_e32 v190, v190, v100
	v_add_f32_e32 v191, v191, v101
	v_add_f32_e32 v190, v190, v102
	v_add_f32_e32 v191, v191, v103
	v_cvt_pk_bf16_f32 v144, v96, v97
	v_cvt_pk_bf16_f32 v145, v98, v99
	v_cvt_pk_bf16_f32 v146, v100, v101
	v_cvt_pk_bf16_f32 v147, v102, v103
	v_sub_f32_e32 v104, v104, v175
	v_sub_f32_e32 v105, v105, v175
	v_sub_f32_e32 v106, v106, v175
	v_sub_f32_e32 v107, v107, v175
	v_sub_f32_e32 v108, v108, v175
	v_sub_f32_e32 v109, v109, v175
	v_sub_f32_e32 v110, v110, v175
	v_sub_f32_e32 v111, v111, v175
	v_exp_f32_e32 v104, v104
	v_exp_f32_e32 v105, v105
	v_exp_f32_e32 v106, v106
	v_exp_f32_e32 v107, v107
	v_exp_f32_e32 v108, v108
	v_exp_f32_e32 v109, v109
	v_exp_f32_e32 v110, v110
	v_exp_f32_e32 v111, v111
	v_add_f32_e32 v190, v190, v104
	v_add_f32_e32 v191, v191, v105
	v_add_f32_e32 v190, v190, v106
	v_add_f32_e32 v191, v191, v107
	v_add_f32_e32 v190, v190, v108
	v_add_f32_e32 v191, v191, v109
	v_add_f32_e32 v190, v190, v110
	v_add_f32_e32 v191, v191, v111
	v_cvt_pk_bf16_f32 v148, v104, v105
	v_cvt_pk_bf16_f32 v149, v106, v107
	v_cvt_pk_bf16_f32 v150, v108, v109
	v_cvt_pk_bf16_f32 v151, v110, v111
	v_sub_f32_e32 v112, v112, v175
	v_sub_f32_e32 v113, v113, v175
	v_sub_f32_e32 v114, v114, v175
	v_sub_f32_e32 v115, v115, v175
	v_sub_f32_e32 v116, v116, v175
	v_sub_f32_e32 v117, v117, v175
	v_sub_f32_e32 v118, v118, v175
	v_sub_f32_e32 v119, v119, v175
	v_exp_f32_e32 v112, v112
	v_exp_f32_e32 v113, v113
	v_exp_f32_e32 v114, v114
	v_exp_f32_e32 v115, v115
	v_exp_f32_e32 v116, v116
	v_exp_f32_e32 v117, v117
	v_exp_f32_e32 v118, v118
	v_exp_f32_e32 v119, v119
	v_add_f32_e32 v190, v190, v112
	v_add_f32_e32 v191, v191, v113
	v_add_f32_e32 v190, v190, v114
	v_add_f32_e32 v191, v191, v115
	v_add_f32_e32 v190, v190, v116
	v_add_f32_e32 v191, v191, v117
	v_add_f32_e32 v190, v190, v118
	v_add_f32_e32 v191, v191, v119
	v_cvt_pk_bf16_f32 v152, v112, v113
	v_cvt_pk_bf16_f32 v153, v114, v115
	v_cvt_pk_bf16_f32 v154, v116, v117
	v_cvt_pk_bf16_f32 v155, v118, v119
	v_sub_f32_e32 v120, v120, v175
	v_sub_f32_e32 v121, v121, v175
	v_sub_f32_e32 v122, v122, v175
	v_sub_f32_e32 v123, v123, v175
	v_sub_f32_e32 v124, v124, v175
	v_sub_f32_e32 v125, v125, v175
	v_sub_f32_e32 v126, v126, v175
	v_sub_f32_e32 v127, v127, v175
	v_exp_f32_e32 v120, v120
	v_exp_f32_e32 v121, v121
	v_exp_f32_e32 v122, v122
	v_exp_f32_e32 v123, v123
	v_exp_f32_e32 v124, v124
	v_exp_f32_e32 v125, v125
	v_exp_f32_e32 v126, v126
	v_exp_f32_e32 v127, v127
	v_add_f32_e32 v190, v190, v120
	v_add_f32_e32 v191, v191, v121
	v_add_f32_e32 v190, v190, v122
	v_add_f32_e32 v191, v191, v123
	v_add_f32_e32 v190, v190, v124
	v_add_f32_e32 v191, v191, v125
	v_add_f32_e32 v190, v190, v126
	v_add_f32_e32 v191, v191, v127
	v_cvt_pk_bf16_f32 v156, v120, v121
	v_cvt_pk_bf16_f32 v157, v122, v123
	v_cvt_pk_bf16_f32 v158, v124, v125
	v_cvt_pk_bf16_f32 v159, v126, v127
	v_add_f32_e32 v190, v190, v191
	v_fma_f32 v167, v167, v174, v190
	s_cbranch_vccz .Lattn_noresc_L2
	s_nop 7
	s_nop 7
	v_pk_mul_f32 v[0:1], v[0:1], v[174:175] op_sel_hi:[1,0]
	v_pk_mul_f32 v[2:3], v[2:3], v[174:175] op_sel_hi:[1,0]
	v_pk_mul_f32 v[4:5], v[4:5], v[174:175] op_sel_hi:[1,0]
	v_pk_mul_f32 v[6:7], v[6:7], v[174:175] op_sel_hi:[1,0]
	v_pk_mul_f32 v[8:9], v[8:9], v[174:175] op_sel_hi:[1,0]
	v_pk_mul_f32 v[10:11], v[10:11], v[174:175] op_sel_hi:[1,0]
	v_pk_mul_f32 v[12:13], v[12:13], v[174:175] op_sel_hi:[1,0]
	v_pk_mul_f32 v[14:15], v[14:15], v[174:175] op_sel_hi:[1,0]
	v_pk_mul_f32 v[16:17], v[16:17], v[174:175] op_sel_hi:[1,0]
	v_pk_mul_f32 v[18:19], v[18:19], v[174:175] op_sel_hi:[1,0]
	v_pk_mul_f32 v[20:21], v[20:21], v[174:175] op_sel_hi:[1,0]
	v_pk_mul_f32 v[22:23], v[22:23], v[174:175] op_sel_hi:[1,0]
	v_pk_mul_f32 v[24:25], v[24:25], v[174:175] op_sel_hi:[1,0]
	v_pk_mul_f32 v[26:27], v[26:27], v[174:175] op_sel_hi:[1,0]
	v_pk_mul_f32 v[28:29], v[28:29], v[174:175] op_sel_hi:[1,0]
	v_pk_mul_f32 v[30:31], v[30:31], v[174:175] op_sel_hi:[1,0]
	v_pk_mul_f32 v[32:33], v[32:33], v[174:175] op_sel_hi:[1,0]
	v_pk_mul_f32 v[34:35], v[34:35], v[174:175] op_sel_hi:[1,0]
	v_pk_mul_f32 v[36:37], v[36:37], v[174:175] op_sel_hi:[1,0]
	v_pk_mul_f32 v[38:39], v[38:39], v[174:175] op_sel_hi:[1,0]
	v_pk_mul_f32 v[40:41], v[40:41], v[174:175] op_sel_hi:[1,0]
	v_pk_mul_f32 v[42:43], v[42:43], v[174:175] op_sel_hi:[1,0]
	v_pk_mul_f32 v[44:45], v[44:45], v[174:175] op_sel_hi:[1,0]
	v_pk_mul_f32 v[46:47], v[46:47], v[174:175] op_sel_hi:[1,0]
	v_pk_mul_f32 v[48:49], v[48:49], v[174:175] op_sel_hi:[1,0]
	v_pk_mul_f32 v[50:51], v[50:51], v[174:175] op_sel_hi:[1,0]
	v_pk_mul_f32 v[52:53], v[52:53], v[174:175] op_sel_hi:[1,0]
	v_pk_mul_f32 v[54:55], v[54:55], v[174:175] op_sel_hi:[1,0]
	v_pk_mul_f32 v[56:57], v[56:57], v[174:175] op_sel_hi:[1,0]
	v_pk_mul_f32 v[58:59], v[58:59], v[174:175] op_sel_hi:[1,0]
	v_pk_mul_f32 v[60:61], v[60:61], v[174:175] op_sel_hi:[1,0]
	v_pk_mul_f32 v[62:63], v[62:63], v[174:175] op_sel_hi:[1,0]
	s_nop 1

.Lattn_tb26:
	ds_read_b128 v[216:219], v187 offset:0
	ds_read_b128 v[220:223], v187 offset:4096
	ds_read_b128 v[224:227], v187 offset:8192
	ds_read_b128 v[228:231], v187 offset:12288
	ds_read_b128 v[208:211], v188 offset:0
	ds_read_b128 v[212:215], v188 offset:4096
	v_max3_f32 v254, v64, v65, v66
	s_add_i32 s2, s42, 7
	v_max3_f32 v255, v80, v81, v82
	s_and_b32 s2, s2, 31
	v_max3_f32 v254, v254, v67, v68
	s_mul_i32 s2, s2, 0x44000
	v_max3_f32 v255, v255, v83, v84
	s_add_i32 m0, s5, 0
	v_max3_f32 v254, v254, v69, v70
	s_add_u32 s40, s26, s2
	v_max3_f32 v255, v255, v85, v86
	s_addc_u32 s41, s27, 0
	v_max3_f32 v254, v254, v71, v72
	global_load_lds_dwordx4 v170, s[40:41]
	v_max3_f32 v255, v255, v87, v88
	s_add_i32 m0, s5, 8192
	v_max3_f32 v254, v254, v73, v74
	s_add_u32 s40, s40, 0x80
	v_max3_f32 v255, v255, v89, v90
	s_addc_u32 s41, s41, 0
	v_max3_f32 v254, v254, v75, v76
	global_load_lds_dwordx4 v170, s[40:41]
	v_max3_f32 v255, v255, v91, v92
	s_add_i32 s2, s42, 5
	v_max3_f32 v254, v254, v77, v78
	s_and_b32 s2, s2, 31
	v_max3_f32 v255, v255, v93, v94
	s_lshl_b32 s2, s2, 7
	v_max3_f32 v254, v254, v79, v95
	s_add_i32 m0, s5, 98304
	v_max_f32_e32 v254, v254, v255
	s_add_u32 s44, s10, s2
	s_addc_u32 s45, s11, 0
	global_load_lds_dwordx4 v172, s[44:45]
	s_add_i32 m0, s5, 106496
	s_add_u32 s44, s44, 0x204000
	s_addc_u32 s45, s45, 0
	global_load_lds_dwordx4 v172, s[44:45]
	v_mov_b32_e32 v255, v254
	s_nop 1
	v_permlane32_swap_b32_e32 v254, v255
	v_max_f32_e32 v254, v254, v255
	v_add_f32_e32 v180, 0x4138aa3b, v175
	v_cmp_gt_f32_e32 vcc, v254, v180
	s_nop 1
	v_cndmask_b32_e32 v180, v175, v254, vcc
	v_sub_f32_e32 v255, v175, v180
	v_exp_f32_e32 v174, v255
	v_mov_b32_e32 v175, v180
	v_sub_f32_e32 v64, v64, v175
	v_sub_f32_e32 v65, v65, v175
	v_sub_f32_e32 v66, v66, v175
	v_sub_f32_e32 v67, v67, v175
	v_sub_f32_e32 v68, v68, v175
	v_sub_f32_e32 v69, v69, v175
	v_sub_f32_e32 v70, v70, v175
	v_sub_f32_e32 v71, v71, v175
	v_exp_f32_e32 v64, v64
	v_exp_f32_e32 v65, v65
	v_exp_f32_e32 v66, v66
	v_exp_f32_e32 v67, v67
	v_exp_f32_e32 v68, v68
	v_exp_f32_e32 v69, v69
	v_exp_f32_e32 v70, v70
	v_exp_f32_e32 v71, v71
	v_add_f32_e32 v190, v64, v65
	v_add_f32_e32 v191, v66, v67
	v_add_f32_e32 v190, v190, v68
	v_add_f32_e32 v191, v191, v69
	v_add_f32_e32 v190, v190, v70
	v_add_f32_e32 v191, v191, v71
	v_cvt_pk_bf16_f32 v144, v64, v65
	v_cvt_pk_bf16_f32 v145, v66, v67
	v_cvt_pk_bf16_f32 v146, v68, v69
	v_cvt_pk_bf16_f32 v147, v70, v71
	v_sub_f32_e32 v72, v72, v175
	v_sub_f32_e32 v73, v73, v175
	v_sub_f32_e32 v74, v74, v175
	v_sub_f32_e32 v75, v75, v175
	v_sub_f32_e32 v76, v76, v175
	v_sub_f32_e32 v77, v77, v175
	v_sub_f32_e32 v78, v78, v175
	v_sub_f32_e32 v79, v79, v175
	v_exp_f32_e32 v72, v72
	v_exp_f32_e32 v73, v73
	v_exp_f32_e32 v74, v74
	v_exp_f32_e32 v75, v75
	v_exp_f32_e32 v76, v76
	v_exp_f32_e32 v77, v77
	v_exp_f32_e32 v78, v78
	v_exp_f32_e32 v79, v79
	v_add_f32_e32 v190, v190, v72
	v_add_f32_e32 v191, v191, v73
	v_add_f32_e32 v190, v190, v74
	v_add_f32_e32 v191, v191, v75
	v_add_f32_e32 v190, v190, v76
	v_add_f32_e32 v191, v191, v77
	v_add_f32_e32 v190, v190, v78
	v_add_f32_e32 v191, v191, v79
	v_cvt_pk_bf16_f32 v148, v72, v73
	v_cvt_pk_bf16_f32 v149, v74, v75
	v_cvt_pk_bf16_f32 v150, v76, v77
	v_cvt_pk_bf16_f32 v151, v78, v79
	v_sub_f32_e32 v80, v80, v175
	v_sub_f32_e32 v81, v81, v175
	v_sub_f32_e32 v82, v82, v175
	v_sub_f32_e32 v83, v83, v175
	v_sub_f32_e32 v84, v84, v175
	v_sub_f32_e32 v85, v85, v175
	v_sub_f32_e32 v86, v86, v175
	v_sub_f32_e32 v87, v87, v175
	v_exp_f32_e32 v80, v80
	v_exp_f32_e32 v81, v81
	v_exp_f32_e32 v82, v82
	v_exp_f32_e32 v83, v83
	v_exp_f32_e32 v84, v84
	v_exp_f32_e32 v85, v85
	v_exp_f32_e32 v86, v86
	v_exp_f32_e32 v87, v87
	v_add_f32_e32 v190, v190, v80
	v_add_f32_e32 v191, v191, v81
	v_add_f32_e32 v190, v190, v82
	v_add_f32_e32 v191, v191, v83
	v_add_f32_e32 v190, v190, v84
	v_add_f32_e32 v191, v191, v85
	v_add_f32_e32 v190, v190, v86
	v_add_f32_e32 v191, v191, v87
	v_cvt_pk_bf16_f32 v152, v80, v81
	v_cvt_pk_bf16_f32 v153, v82, v83
	v_cvt_pk_bf16_f32 v154, v84, v85
	v_cvt_pk_bf16_f32 v155, v86, v87
	v_sub_f32_e32 v88, v88, v175
	v_sub_f32_e32 v89, v89, v175
	v_sub_f32_e32 v90, v90, v175
	v_sub_f32_e32 v91, v91, v175
	v_sub_f32_e32 v92, v92, v175
	v_sub_f32_e32 v93, v93, v175
	v_sub_f32_e32 v94, v94, v175
	v_sub_f32_e32 v95, v95, v175
	v_exp_f32_e32 v88, v88
	v_exp_f32_e32 v89, v89
	v_exp_f32_e32 v90, v90
	v_exp_f32_e32 v91, v91
	v_exp_f32_e32 v92, v92
	v_exp_f32_e32 v93, v93
	v_exp_f32_e32 v94, v94
	v_exp_f32_e32 v95, v95
	v_add_f32_e32 v190, v190, v88
	v_add_f32_e32 v191, v191, v89
	v_add_f32_e32 v190, v190, v90
	v_add_f32_e32 v191, v191, v91
	v_add_f32_e32 v190, v190, v92
	v_add_f32_e32 v191, v191, v93
	v_add_f32_e32 v190, v190, v94
	v_add_f32_e32 v191, v191, v95
	v_cvt_pk_bf16_f32 v156, v88, v89
	v_cvt_pk_bf16_f32 v157, v90, v91
	v_cvt_pk_bf16_f32 v158, v92, v93
	v_cvt_pk_bf16_f32 v159, v94, v95
	v_add_f32_e32 v190, v190, v191
	v_fma_f32 v167, v167, v174, v190
	s_cbranch_vccz .Lattn_noresc_L3
	s_nop 7
	s_nop 7
	v_pk_mul_f32 v[0:1], v[0:1], v[174:175] op_sel_hi:[1,0]
	v_pk_mul_f32 v[2:3], v[2:3], v[174:175] op_sel_hi:[1,0]
	v_pk_mul_f32 v[4:5], v[4:5], v[174:175] op_sel_hi:[1,0]
	v_pk_mul_f32 v[6:7], v[6:7], v[174:175] op_sel_hi:[1,0]
	v_pk_mul_f32 v[8:9], v[8:9], v[174:175] op_sel_hi:[1,0]
	v_pk_mul_f32 v[10:11], v[10:11], v[174:175] op_sel_hi:[1,0]
	v_pk_mul_f32 v[12:13], v[12:13], v[174:175] op_sel_hi:[1,0]
	v_pk_mul_f32 v[14:15], v[14:15], v[174:175] op_sel_hi:[1,0]
	v_pk_mul_f32 v[16:17], v[16:17], v[174:175] op_sel_hi:[1,0]
	v_pk_mul_f32 v[18:19], v[18:19], v[174:175] op_sel_hi:[1,0]
	v_pk_mul_f32 v[20:21], v[20:21], v[174:175] op_sel_hi:[1,0]
	v_pk_mul_f32 v[22:23], v[22:23], v[174:175] op_sel_hi:[1,0]
	v_pk_mul_f32 v[24:25], v[24:25], v[174:175] op_sel_hi:[1,0]
	v_pk_mul_f32 v[26:27], v[26:27], v[174:175] op_sel_hi:[1,0]
	v_pk_mul_f32 v[28:29], v[28:29], v[174:175] op_sel_hi:[1,0]
	v_pk_mul_f32 v[30:31], v[30:31], v[174:175] op_sel_hi:[1,0]
	v_pk_mul_f32 v[32:33], v[32:33], v[174:175] op_sel_hi:[1,0]
	v_pk_mul_f32 v[34:35], v[34:35], v[174:175] op_sel_hi:[1,0]
	v_pk_mul_f32 v[36:37], v[36:37], v[174:175] op_sel_hi:[1,0]
	v_pk_mul_f32 v[38:39], v[38:39], v[174:175] op_sel_hi:[1,0]
	v_pk_mul_f32 v[40:41], v[40:41], v[174:175] op_sel_hi:[1,0]
	v_pk_mul_f32 v[42:43], v[42:43], v[174:175] op_sel_hi:[1,0]
	v_pk_mul_f32 v[44:45], v[44:45], v[174:175] op_sel_hi:[1,0]
	v_pk_mul_f32 v[46:47], v[46:47], v[174:175] op_sel_hi:[1,0]
	v_pk_mul_f32 v[48:49], v[48:49], v[174:175] op_sel_hi:[1,0]
	v_pk_mul_f32 v[50:51], v[50:51], v[174:175] op_sel_hi:[1,0]
	v_pk_mul_f32 v[52:53], v[52:53], v[174:175] op_sel_hi:[1,0]
	v_pk_mul_f32 v[54:55], v[54:55], v[174:175] op_sel_hi:[1,0]
	v_pk_mul_f32 v[56:57], v[56:57], v[174:175] op_sel_hi:[1,0]
	v_pk_mul_f32 v[58:59], v[58:59], v[174:175] op_sel_hi:[1,0]
	v_pk_mul_f32 v[60:61], v[60:61], v[174:175] op_sel_hi:[1,0]
	v_pk_mul_f32 v[62:63], v[62:63], v[174:175] op_sel_hi:[1,0]
	s_nop 1

.Lattn_tb28:
	ds_read_b128 v[216:219], v187 offset:16384
	ds_read_b128 v[220:223], v187 offset:20480
	ds_read_b128 v[224:227], v187 offset:24576
	ds_read_b128 v[228:231], v187 offset:28672
	ds_read_b128 v[208:211], v188 offset:16384
	ds_read_b128 v[212:215], v188 offset:20480
	v_max3_f32 v254, v96, v97, v98
	s_add_i32 s2, s42, 2
	v_max3_f32 v255, v112, v113, v114
	s_and_b32 s2, s2, 31
	v_max3_f32 v254, v254, v99, v100
	s_lshl_b32 s2, s2, 7
	v_max3_f32 v255, v255, v115, v116
	s_add_i32 m0, s5, 114688
	v_max3_f32 v254, v254, v101, v102
	s_add_u32 s44, s10, s2
	v_max3_f32 v255, v255, v117, v118
	s_addc_u32 s45, s11, 0
	v_max3_f32 v254, v254, v103, v104
	global_load_lds_dwordx4 v172, s[44:45]
	v_max3_f32 v255, v255, v119, v120
	s_add_i32 m0, s5, 122880
	v_max3_f32 v254, v254, v105, v106
	s_add_u32 s44, s44, 0x204000
	v_max3_f32 v255, v255, v121, v122
	s_addc_u32 s45, s45, 0
	v_max3_f32 v254, v254, v107, v108
	global_load_lds_dwordx4 v172, s[44:45]
	v_max3_f32 v255, v255, v123, v124
	v_max3_f32 v254, v254, v109, v110
	v_max3_f32 v255, v255, v125, v126
	v_max3_f32 v254, v254, v111, v127
	v_max_f32_e32 v254, v254, v255
	v_mov_b32_e32 v255, v254
	s_nop 1
	v_permlane32_swap_b32_e32 v254, v255
	v_max_f32_e32 v254, v254, v255
	v_add_f32_e32 v180, 0x4138aa3b, v175
	v_cmp_gt_f32_e32 vcc, v254, v180
	s_nop 1
	v_cndmask_b32_e32 v180, v175, v254, vcc
	v_sub_f32_e32 v255, v175, v180
	v_exp_f32_e32 v174, v255
	v_mov_b32_e32 v175, v180
	v_sub_f32_e32 v96, v96, v175
	v_sub_f32_e32 v97, v97, v175
	v_sub_f32_e32 v98, v98, v175
	v_sub_f32_e32 v99, v99, v175
	v_sub_f32_e32 v100, v100, v175
	v_sub_f32_e32 v101, v101, v175
	v_sub_f32_e32 v102, v102, v175
	v_sub_f32_e32 v103, v103, v175
	v_exp_f32_e32 v96, v96
	v_exp_f32_e32 v97, v97
	v_exp_f32_e32 v98, v98
	v_exp_f32_e32 v99, v99
	v_exp_f32_e32 v100, v100
	v_exp_f32_e32 v101, v101
	v_exp_f32_e32 v102, v102
	v_exp_f32_e32 v103, v103
	v_add_f32_e32 v190, v96, v97
	v_add_f32_e32 v191, v98, v99
	v_add_f32_e32 v190, v190, v100
	v_add_f32_e32 v191, v191, v101
	v_add_f32_e32 v190, v190, v102
	v_add_f32_e32 v191, v191, v103
	v_cvt_pk_bf16_f32 v144, v96, v97
	v_cvt_pk_bf16_f32 v145, v98, v99
	v_cvt_pk_bf16_f32 v146, v100, v101
	v_cvt_pk_bf16_f32 v147, v102, v103
	v_sub_f32_e32 v104, v104, v175
	v_sub_f32_e32 v105, v105, v175
	v_sub_f32_e32 v106, v106, v175
	v_sub_f32_e32 v107, v107, v175
	v_sub_f32_e32 v108, v108, v175
	v_sub_f32_e32 v109, v109, v175
	v_sub_f32_e32 v110, v110, v175
	v_sub_f32_e32 v111, v111, v175
	v_exp_f32_e32 v104, v104
	v_exp_f32_e32 v105, v105
	v_exp_f32_e32 v106, v106
	v_exp_f32_e32 v107, v107
	v_exp_f32_e32 v108, v108
	v_exp_f32_e32 v109, v109
	v_exp_f32_e32 v110, v110
	v_exp_f32_e32 v111, v111
	v_add_f32_e32 v190, v190, v104
	v_add_f32_e32 v191, v191, v105
	v_add_f32_e32 v190, v190, v106
	v_add_f32_e32 v191, v191, v107
	v_add_f32_e32 v190, v190, v108
	v_add_f32_e32 v191, v191, v109
	v_add_f32_e32 v190, v190, v110
	v_add_f32_e32 v191, v191, v111
	v_cvt_pk_bf16_f32 v148, v104, v105
	v_cvt_pk_bf16_f32 v149, v106, v107
	v_cvt_pk_bf16_f32 v150, v108, v109
	v_cvt_pk_bf16_f32 v151, v110, v111
	v_sub_f32_e32 v112, v112, v175
	v_sub_f32_e32 v113, v113, v175
	v_sub_f32_e32 v114, v114, v175
	v_sub_f32_e32 v115, v115, v175
	v_sub_f32_e32 v116, v116, v175
	v_sub_f32_e32 v117, v117, v175
	v_sub_f32_e32 v118, v118, v175
	v_sub_f32_e32 v119, v119, v175
	v_exp_f32_e32 v112, v112
	v_exp_f32_e32 v113, v113
	v_exp_f32_e32 v114, v114
	v_exp_f32_e32 v115, v115
	v_exp_f32_e32 v116, v116
	v_exp_f32_e32 v117, v117
	v_exp_f32_e32 v118, v118
	v_exp_f32_e32 v119, v119
	v_add_f32_e32 v190, v190, v112
	v_add_f32_e32 v191, v191, v113
	v_add_f32_e32 v190, v190, v114
	v_add_f32_e32 v191, v191, v115
	v_add_f32_e32 v190, v190, v116
	v_add_f32_e32 v191, v191, v117
	v_add_f32_e32 v190, v190, v118
	v_add_f32_e32 v191, v191, v119
	v_cvt_pk_bf16_f32 v152, v112, v113
	v_cvt_pk_bf16_f32 v153, v114, v115
	v_cvt_pk_bf16_f32 v154, v116, v117
	v_cvt_pk_bf16_f32 v155, v118, v119
	v_sub_f32_e32 v120, v120, v175
	v_sub_f32_e32 v121, v121, v175
	v_sub_f32_e32 v122, v122, v175
	v_sub_f32_e32 v123, v123, v175
	v_sub_f32_e32 v124, v124, v175
	v_sub_f32_e32 v125, v125, v175
	v_sub_f32_e32 v126, v126, v175
	v_sub_f32_e32 v127, v127, v175
	v_exp_f32_e32 v120, v120
	v_exp_f32_e32 v121, v121
	v_exp_f32_e32 v122, v122
	v_exp_f32_e32 v123, v123
	v_exp_f32_e32 v124, v124
	v_exp_f32_e32 v125, v125
	v_exp_f32_e32 v126, v126
	v_exp_f32_e32 v127, v127
	v_add_f32_e32 v190, v190, v120
	v_add_f32_e32 v191, v191, v121
	v_add_f32_e32 v190, v190, v122
	v_add_f32_e32 v191, v191, v123
	v_add_f32_e32 v190, v190, v124
	v_add_f32_e32 v191, v191, v125
	v_add_f32_e32 v190, v190, v126
	v_add_f32_e32 v191, v191, v127
	v_cvt_pk_bf16_f32 v156, v120, v121
	v_cvt_pk_bf16_f32 v157, v122, v123
	v_cvt_pk_bf16_f32 v158, v124, v125
	v_cvt_pk_bf16_f32 v159, v126, v127
	v_add_f32_e32 v190, v190, v191
	v_fma_f32 v167, v167, v174, v190
	s_cbranch_vccz .Lattn_noresc_T29
	s_nop 7
	s_nop 7
	v_pk_mul_f32 v[0:1], v[0:1], v[174:175] op_sel_hi:[1,0]
	v_pk_mul_f32 v[2:3], v[2:3], v[174:175] op_sel_hi:[1,0]
	v_pk_mul_f32 v[4:5], v[4:5], v[174:175] op_sel_hi:[1,0]
	v_pk_mul_f32 v[6:7], v[6:7], v[174:175] op_sel_hi:[1,0]
	v_pk_mul_f32 v[8:9], v[8:9], v[174:175] op_sel_hi:[1,0]
	v_pk_mul_f32 v[10:11], v[10:11], v[174:175] op_sel_hi:[1,0]
	v_pk_mul_f32 v[12:13], v[12:13], v[174:175] op_sel_hi:[1,0]
	v_pk_mul_f32 v[14:15], v[14:15], v[174:175] op_sel_hi:[1,0]
	v_pk_mul_f32 v[16:17], v[16:17], v[174:175] op_sel_hi:[1,0]
	v_pk_mul_f32 v[18:19], v[18:19], v[174:175] op_sel_hi:[1,0]
	v_pk_mul_f32 v[20:21], v[20:21], v[174:175] op_sel_hi:[1,0]
	v_pk_mul_f32 v[22:23], v[22:23], v[174:175] op_sel_hi:[1,0]
	v_pk_mul_f32 v[24:25], v[24:25], v[174:175] op_sel_hi:[1,0]
	v_pk_mul_f32 v[26:27], v[26:27], v[174:175] op_sel_hi:[1,0]
	v_pk_mul_f32 v[28:29], v[28:29], v[174:175] op_sel_hi:[1,0]
	v_pk_mul_f32 v[30:31], v[30:31], v[174:175] op_sel_hi:[1,0]
	v_pk_mul_f32 v[32:33], v[32:33], v[174:175] op_sel_hi:[1,0]
	v_pk_mul_f32 v[34:35], v[34:35], v[174:175] op_sel_hi:[1,0]
	v_pk_mul_f32 v[36:37], v[36:37], v[174:175] op_sel_hi:[1,0]
	v_pk_mul_f32 v[38:39], v[38:39], v[174:175] op_sel_hi:[1,0]
	v_pk_mul_f32 v[40:41], v[40:41], v[174:175] op_sel_hi:[1,0]
	v_pk_mul_f32 v[42:43], v[42:43], v[174:175] op_sel_hi:[1,0]
	v_pk_mul_f32 v[44:45], v[44:45], v[174:175] op_sel_hi:[1,0]
	v_pk_mul_f32 v[46:47], v[46:47], v[174:175] op_sel_hi:[1,0]
	v_pk_mul_f32 v[48:49], v[48:49], v[174:175] op_sel_hi:[1,0]
	v_pk_mul_f32 v[50:51], v[50:51], v[174:175] op_sel_hi:[1,0]
	v_pk_mul_f32 v[52:53], v[52:53], v[174:175] op_sel_hi:[1,0]
	v_pk_mul_f32 v[54:55], v[54:55], v[174:175] op_sel_hi:[1,0]
	v_pk_mul_f32 v[56:57], v[56:57], v[174:175] op_sel_hi:[1,0]
	v_pk_mul_f32 v[58:59], v[58:59], v[174:175] op_sel_hi:[1,0]
	v_pk_mul_f32 v[60:61], v[60:61], v[174:175] op_sel_hi:[1,0]
	v_pk_mul_f32 v[62:63], v[62:63], v[174:175] op_sel_hi:[1,0]
	s_nop 1
.Lattn_noresc_T29:
.Lattn_top_T30:
	s_cmp_lg_u32 s14, 0
	s_cbranch_scc1 .Lattn_tb29
	s_waitcnt vmcnt(2)
	s_barrier

.Lattn_tb30:
	ds_read_b128 v[216:219], v187 offset:32768
	ds_read_b128 v[220:223], v187 offset:36864
	ds_read_b128 v[224:227], v187 offset:40960
	ds_read_b128 v[228:231], v187 offset:45056
	ds_read_b128 v[208:211], v188 offset:32768
	ds_read_b128 v[212:215], v188 offset:36864
	v_max3_f32 v254, v64, v65, v66
	v_readlane_b32 s2, v253, 52
	s_add_i32 s36, s46, 1
	s_mul_i32 s36, s36, s56
	s_add_i32 s36, s36, s0
	s_cmp_lg_u32 s2, 0
	s_cselect_b32 s2, 1, 0
	s_cmpk_lt_i32 s36, 0x400
	s_cselect_b32 s36, 1, 0
	s_and_b32 s35, s2, s36
	v_max3_f32 v255, v80, v81, v82
	s_cmp_lg_u32 s35, 0
	s_cbranch_scc0 .Lattn_pfka_s
	s_add_i32 s2, s31, 0
	s_and_b32 s2, s2, 31
	s_mul_i32 s2, s2, 0x44000
	s_add_i32 m0, s5, 0
	s_add_u32 s40, s26, s2
	s_addc_u32 s41, s27, 0
	s_add_u32 s40, s40, 0x1100000
	s_addc_u32 s41, s41, 0
	global_load_lds_dwordx4 v170, s[40:41]
	s_add_i32 m0, s5, 8192
	s_add_u32 s40, s40, 0x80
	s_addc_u32 s41, s41, 0
	global_load_lds_dwordx4 v170, s[40:41]
.Lattn_pfka_s:
	v_max3_f32 v254, v254, v67, v68
	s_cmp_lg_u32 s35, 0
	s_cbranch_scc0 .Lattn_pfkb_s
	s_add_i32 s2, s31, 1
	s_and_b32 s2, s2, 31
	s_mul_i32 s2, s2, 0x44000
	s_add_i32 m0, s5, 16384
	s_add_u32 s40, s26, s2
	s_addc_u32 s41, s27, 0
	s_add_u32 s40, s40, 0x1100000
	s_addc_u32 s41, s41, 0
	global_load_lds_dwordx4 v170, s[40:41]
	s_add_i32 m0, s5, 24576
	s_add_u32 s40, s40, 0x80
	s_addc_u32 s41, s41, 0
	global_load_lds_dwordx4 v170, s[40:41]
.Lattn_pfkb_s:
	v_max3_f32 v255, v255, v83, v84
	s_cmp_lg_u32 s35, 0
	s_cbranch_scc0 .Lattn_pfvt_s
	s_add_i32 s2, s31, 0
	s_and_b32 s2, s2, 31
	s_lshl_b32 s2, s2, 7
	s_add_i32 m0, s5, 65536
	s_add_u32 s44, s10, s2
	s_addc_u32 s45, s11, 0
	s_add_u32 s44, s44, 0x2000
	s_addc_u32 s45, s45, 0
	global_load_lds_dwordx4 v172, s[44:45]
	s_add_i32 m0, s5, 73728
	s_add_u32 s44, s44, 0x204000
	s_addc_u32 s45, s45, 0
	global_load_lds_dwordx4 v172, s[44:45]
.Lattn_pfvt_s:
	v_max3_f32 v254, v254, v69, v70
	v_max3_f32 v255, v255, v85, v86
	v_max3_f32 v254, v254, v71, v72
	v_max3_f32 v255, v255, v87, v88
	v_max3_f32 v254, v254, v73, v74
	v_max3_f32 v255, v255, v89, v90
	v_max3_f32 v254, v254, v75, v76
	v_max3_f32 v255, v255, v91, v92
	v_max3_f32 v254, v254, v77, v78
	v_max3_f32 v255, v255, v93, v94
	v_max3_f32 v254, v254, v79, v95
	v_max_f32_e32 v254, v254, v255
	v_mov_b32_e32 v255, v254
	s_nop 1
	v_permlane32_swap_b32_e32 v254, v255
	v_max_f32_e32 v254, v254, v255
	v_add_f32_e32 v180, 0x4138aa3b, v175
	v_cmp_gt_f32_e32 vcc, v254, v180
	s_nop 1
	v_cndmask_b32_e32 v180, v175, v254, vcc
	v_sub_f32_e32 v255, v175, v180
	v_exp_f32_e32 v174, v255
	v_mov_b32_e32 v175, v180
	v_sub_f32_e32 v64, v64, v175
	v_sub_f32_e32 v65, v65, v175
	v_sub_f32_e32 v66, v66, v175
	v_sub_f32_e32 v67, v67, v175
	v_sub_f32_e32 v68, v68, v175
	v_sub_f32_e32 v69, v69, v175
	v_sub_f32_e32 v70, v70, v175
	v_sub_f32_e32 v71, v71, v175
	v_exp_f32_e32 v64, v64
	v_exp_f32_e32 v65, v65
	v_exp_f32_e32 v66, v66
	v_exp_f32_e32 v67, v67
	v_exp_f32_e32 v68, v68
	v_exp_f32_e32 v69, v69
	v_exp_f32_e32 v70, v70
	v_exp_f32_e32 v71, v71
	v_add_f32_e32 v190, v64, v65
	v_add_f32_e32 v191, v66, v67
	v_add_f32_e32 v190, v190, v68
	v_add_f32_e32 v191, v191, v69
	v_add_f32_e32 v190, v190, v70
	v_add_f32_e32 v191, v191, v71
	v_cvt_pk_bf16_f32 v144, v64, v65
	v_cvt_pk_bf16_f32 v145, v66, v67
	v_cvt_pk_bf16_f32 v146, v68, v69
	v_cvt_pk_bf16_f32 v147, v70, v71
	v_sub_f32_e32 v72, v72, v175
	v_sub_f32_e32 v73, v73, v175
	v_sub_f32_e32 v74, v74, v175
	v_sub_f32_e32 v75, v75, v175
	v_sub_f32_e32 v76, v76, v175
	v_sub_f32_e32 v77, v77, v175
	v_sub_f32_e32 v78, v78, v175
	v_sub_f32_e32 v79, v79, v175
	v_exp_f32_e32 v72, v72
	v_exp_f32_e32 v73, v73
	v_exp_f32_e32 v74, v74
	v_exp_f32_e32 v75, v75
	v_exp_f32_e32 v76, v76
	v_exp_f32_e32 v77, v77
	v_exp_f32_e32 v78, v78
	v_exp_f32_e32 v79, v79
	v_add_f32_e32 v190, v190, v72
	v_add_f32_e32 v191, v191, v73
	v_add_f32_e32 v190, v190, v74
	v_add_f32_e32 v191, v191, v75
	v_add_f32_e32 v190, v190, v76
	v_add_f32_e32 v191, v191, v77
	v_add_f32_e32 v190, v190, v78
	v_add_f32_e32 v191, v191, v79
	v_cvt_pk_bf16_f32 v148, v72, v73
	v_cvt_pk_bf16_f32 v149, v74, v75
	v_cvt_pk_bf16_f32 v150, v76, v77
	v_cvt_pk_bf16_f32 v151, v78, v79
	v_sub_f32_e32 v80, v80, v175
	v_sub_f32_e32 v81, v81, v175
	v_sub_f32_e32 v82, v82, v175
	v_sub_f32_e32 v83, v83, v175
	v_sub_f32_e32 v84, v84, v175
	v_sub_f32_e32 v85, v85, v175
	v_sub_f32_e32 v86, v86, v175
	v_sub_f32_e32 v87, v87, v175
	v_exp_f32_e32 v80, v80
	v_exp_f32_e32 v81, v81
	v_exp_f32_e32 v82, v82
	v_exp_f32_e32 v83, v83
	v_exp_f32_e32 v84, v84
	v_exp_f32_e32 v85, v85
	v_exp_f32_e32 v86, v86
	v_exp_f32_e32 v87, v87
	v_add_f32_e32 v190, v190, v80
	v_add_f32_e32 v191, v191, v81
	v_add_f32_e32 v190, v190, v82
	v_add_f32_e32 v191, v191, v83
	v_add_f32_e32 v190, v190, v84
	v_add_f32_e32 v191, v191, v85
	v_add_f32_e32 v190, v190, v86
	v_add_f32_e32 v191, v191, v87
	v_cvt_pk_bf16_f32 v152, v80, v81
	v_cvt_pk_bf16_f32 v153, v82, v83
	v_cvt_pk_bf16_f32 v154, v84, v85
	v_cvt_pk_bf16_f32 v155, v86, v87
	v_sub_f32_e32 v88, v88, v175
	v_sub_f32_e32 v89, v89, v175
	v_sub_f32_e32 v90, v90, v175
	v_sub_f32_e32 v91, v91, v175
	v_sub_f32_e32 v92, v92, v175
	v_sub_f32_e32 v93, v93, v175
	v_sub_f32_e32 v94, v94, v175
	v_sub_f32_e32 v95, v95, v175
	v_exp_f32_e32 v88, v88
	v_exp_f32_e32 v89, v89
	v_exp_f32_e32 v90, v90
	v_exp_f32_e32 v91, v91
	v_exp_f32_e32 v92, v92
	v_exp_f32_e32 v93, v93
	v_exp_f32_e32 v94, v94
	v_exp_f32_e32 v95, v95
	v_add_f32_e32 v190, v190, v88
	v_add_f32_e32 v191, v191, v89
	v_add_f32_e32 v190, v190, v90
	v_add_f32_e32 v191, v191, v91
	v_add_f32_e32 v190, v190, v92
	v_add_f32_e32 v191, v191, v93
	v_add_f32_e32 v190, v190, v94
	v_add_f32_e32 v191, v191, v95
	v_cvt_pk_bf16_f32 v156, v88, v89
	v_cvt_pk_bf16_f32 v157, v90, v91
	v_cvt_pk_bf16_f32 v158, v92, v93
	v_cvt_pk_bf16_f32 v159, v94, v95
	v_add_f32_e32 v190, v190, v191
	v_fma_f32 v167, v167, v174, v190
	s_cbranch_vccz .Lattn_noresc_T30
	s_nop 7
	s_nop 7
	v_pk_mul_f32 v[0:1], v[0:1], v[174:175] op_sel_hi:[1,0]
	v_pk_mul_f32 v[2:3], v[2:3], v[174:175] op_sel_hi:[1,0]
	v_pk_mul_f32 v[4:5], v[4:5], v[174:175] op_sel_hi:[1,0]
	v_pk_mul_f32 v[6:7], v[6:7], v[174:175] op_sel_hi:[1,0]
	v_pk_mul_f32 v[8:9], v[8:9], v[174:175] op_sel_hi:[1,0]
	v_pk_mul_f32 v[10:11], v[10:11], v[174:175] op_sel_hi:[1,0]
	v_pk_mul_f32 v[12:13], v[12:13], v[174:175] op_sel_hi:[1,0]
	v_pk_mul_f32 v[14:15], v[14:15], v[174:175] op_sel_hi:[1,0]
	v_pk_mul_f32 v[16:17], v[16:17], v[174:175] op_sel_hi:[1,0]
	v_pk_mul_f32 v[18:19], v[18:19], v[174:175] op_sel_hi:[1,0]
	v_pk_mul_f32 v[20:21], v[20:21], v[174:175] op_sel_hi:[1,0]
	v_pk_mul_f32 v[22:23], v[22:23], v[174:175] op_sel_hi:[1,0]
	v_pk_mul_f32 v[24:25], v[24:25], v[174:175] op_sel_hi:[1,0]
	v_pk_mul_f32 v[26:27], v[26:27], v[174:175] op_sel_hi:[1,0]
	v_pk_mul_f32 v[28:29], v[28:29], v[174:175] op_sel_hi:[1,0]
	v_pk_mul_f32 v[30:31], v[30:31], v[174:175] op_sel_hi:[1,0]
	v_pk_mul_f32 v[32:33], v[32:33], v[174:175] op_sel_hi:[1,0]
	v_pk_mul_f32 v[34:35], v[34:35], v[174:175] op_sel_hi:[1,0]
	v_pk_mul_f32 v[36:37], v[36:37], v[174:175] op_sel_hi:[1,0]
	v_pk_mul_f32 v[38:39], v[38:39], v[174:175] op_sel_hi:[1,0]
	v_pk_mul_f32 v[40:41], v[40:41], v[174:175] op_sel_hi:[1,0]
	v_pk_mul_f32 v[42:43], v[42:43], v[174:175] op_sel_hi:[1,0]
	v_pk_mul_f32 v[44:45], v[44:45], v[174:175] op_sel_hi:[1,0]
	v_pk_mul_f32 v[46:47], v[46:47], v[174:175] op_sel_hi:[1,0]
	v_pk_mul_f32 v[48:49], v[48:49], v[174:175] op_sel_hi:[1,0]
	v_pk_mul_f32 v[50:51], v[50:51], v[174:175] op_sel_hi:[1,0]
	v_pk_mul_f32 v[52:53], v[52:53], v[174:175] op_sel_hi:[1,0]
	v_pk_mul_f32 v[54:55], v[54:55], v[174:175] op_sel_hi:[1,0]
	v_pk_mul_f32 v[56:57], v[56:57], v[174:175] op_sel_hi:[1,0]
	v_pk_mul_f32 v[58:59], v[58:59], v[174:175] op_sel_hi:[1,0]
	v_pk_mul_f32 v[60:61], v[60:61], v[174:175] op_sel_hi:[1,0]
	v_pk_mul_f32 v[62:63], v[62:63], v[174:175] op_sel_hi:[1,0]
	s_nop 1
.Lattn_noresc_T30:
.Lattn_top_T31:
	s_cmp_lg_u32 s14, 0
	s_cbranch_scc1 .Lattn_tb31
	s_cmp_lg_u32 s35, 0
	s_cbranch_scc1 .Lattn_tb31_w6
	s_waitcnt vmcnt(0)
	s_branch .Lattn_tb31_wd

.Lattn_tb32:
	ds_read_b128 v[208:211], v187 offset:49152
	ds_read_b128 v[212:215], v187 offset:53248
	ds_read_b128 v[216:219], v187 offset:57344
	ds_read_b128 v[220:223], v187 offset:61440
	ds_read_b128 v[224:227], v188 offset:49152
	ds_read_b128 v[228:231], v188 offset:53248
	v_max3_f32 v254, v96, v97, v98
	s_cmp_lg_u32 s35, 0
	s_cbranch_scc0 .Lattn_pfq_s
	s_movk_i32 s2, 0x1100
	s_lshl_b32 s36, s14, 1
	v_mad_u32_u24 v72, v168, s2, v192
	s_add_i32 s36, s36, s30
	s_add_i32 s36, s36, 0x1100000
	s_nop 0
	v_add_u32_e32 v72, s36, v72
	s_nop 0
	global_load_dwordx4 v[64:67], v72, s[6:7]
	global_load_dwordx4 v[68:71], v72, s[6:7] offset:32
	global_load_dwordx4 v[136:139], v72, s[6:7] offset:64
	global_load_dwordx4 v[140:143], v72, s[6:7] offset:96
.Lattn_pfq_s:
	v_max3_f32 v255, v112, v113, v114
	v_max3_f32 v254, v254, v99, v100
	v_max3_f32 v255, v255, v115, v116
	v_max3_f32 v254, v254, v101, v102
	v_max3_f32 v255, v255, v117, v118
	v_max3_f32 v254, v254, v103, v104
	v_max3_f32 v255, v255, v119, v120
	v_max3_f32 v254, v254, v105, v106
	v_max3_f32 v255, v255, v121, v122
	v_max3_f32 v254, v254, v107, v108
	v_max3_f32 v255, v255, v123, v124
	v_max3_f32 v254, v254, v109, v110
	v_max3_f32 v255, v255, v125, v126
	v_max3_f32 v254, v254, v111, v127
	v_max_f32_e32 v254, v254, v255
	v_mov_b32_e32 v255, v254
	s_nop 1
	v_permlane32_swap_b32_e32 v254, v255
	v_max_f32_e32 v254, v254, v255
	v_add_f32_e32 v180, 0x4138aa3b, v175
	v_cmp_gt_f32_e32 vcc, v254, v180
	s_nop 1
	v_cndmask_b32_e32 v180, v175, v254, vcc
	v_sub_f32_e32 v255, v175, v180
	v_exp_f32_e32 v174, v255
	v_mov_b32_e32 v175, v180
	v_sub_f32_e32 v96, v96, v175
	v_sub_f32_e32 v97, v97, v175
	v_sub_f32_e32 v98, v98, v175
	v_sub_f32_e32 v99, v99, v175
	v_sub_f32_e32 v100, v100, v175
	v_sub_f32_e32 v101, v101, v175
	v_sub_f32_e32 v102, v102, v175
	v_sub_f32_e32 v103, v103, v175
	v_exp_f32_e32 v96, v96
	v_exp_f32_e32 v97, v97
	v_exp_f32_e32 v98, v98
	v_exp_f32_e32 v99, v99
	v_exp_f32_e32 v100, v100
	v_exp_f32_e32 v101, v101
	v_exp_f32_e32 v102, v102
	v_exp_f32_e32 v103, v103
	v_add_f32_e32 v190, v96, v97
	v_add_f32_e32 v191, v98, v99
	v_add_f32_e32 v190, v190, v100
	v_add_f32_e32 v191, v191, v101
	v_add_f32_e32 v190, v190, v102
	v_add_f32_e32 v191, v191, v103
	v_cvt_pk_bf16_f32 v144, v96, v97
	v_cvt_pk_bf16_f32 v145, v98, v99
	v_cvt_pk_bf16_f32 v146, v100, v101
	v_cvt_pk_bf16_f32 v147, v102, v103
	v_sub_f32_e32 v104, v104, v175
	v_sub_f32_e32 v105, v105, v175
	v_sub_f32_e32 v106, v106, v175
	v_sub_f32_e32 v107, v107, v175
	v_sub_f32_e32 v108, v108, v175
	v_sub_f32_e32 v109, v109, v175
	v_sub_f32_e32 v110, v110, v175
	v_sub_f32_e32 v111, v111, v175
	v_exp_f32_e32 v104, v104
	v_exp_f32_e32 v105, v105
	v_exp_f32_e32 v106, v106
	v_exp_f32_e32 v107, v107
	v_exp_f32_e32 v108, v108
	v_exp_f32_e32 v109, v109
	v_exp_f32_e32 v110, v110
	v_exp_f32_e32 v111, v111
	v_add_f32_e32 v190, v190, v104
	v_add_f32_e32 v191, v191, v105
	v_add_f32_e32 v190, v190, v106
	v_add_f32_e32 v191, v191, v107
	v_add_f32_e32 v190, v190, v108
	v_add_f32_e32 v191, v191, v109
	v_add_f32_e32 v190, v190, v110
	v_add_f32_e32 v191, v191, v111
	v_cvt_pk_bf16_f32 v148, v104, v105
	v_cvt_pk_bf16_f32 v149, v106, v107
	v_cvt_pk_bf16_f32 v150, v108, v109
	v_cvt_pk_bf16_f32 v151, v110, v111
	v_sub_f32_e32 v112, v112, v175
	v_sub_f32_e32 v113, v113, v175
	v_sub_f32_e32 v114, v114, v175
	v_sub_f32_e32 v115, v115, v175
	v_sub_f32_e32 v116, v116, v175
	v_sub_f32_e32 v117, v117, v175
	v_sub_f32_e32 v118, v118, v175
	v_sub_f32_e32 v119, v119, v175
	v_exp_f32_e32 v112, v112
	v_exp_f32_e32 v113, v113
	v_exp_f32_e32 v114, v114
	v_exp_f32_e32 v115, v115
	v_exp_f32_e32 v116, v116
	v_exp_f32_e32 v117, v117
	v_exp_f32_e32 v118, v118
	v_exp_f32_e32 v119, v119
	v_add_f32_e32 v190, v190, v112
	v_add_f32_e32 v191, v191, v113
	v_add_f32_e32 v190, v190, v114
	v_add_f32_e32 v191, v191, v115
	v_add_f32_e32 v190, v190, v116
	v_add_f32_e32 v191, v191, v117
	v_add_f32_e32 v190, v190, v118
	v_add_f32_e32 v191, v191, v119
	v_cvt_pk_bf16_f32 v152, v112, v113
	v_cvt_pk_bf16_f32 v153, v114, v115
	v_cvt_pk_bf16_f32 v154, v116, v117
	v_cvt_pk_bf16_f32 v155, v118, v119
	v_sub_f32_e32 v120, v120, v175
	v_sub_f32_e32 v121, v121, v175
	v_sub_f32_e32 v122, v122, v175
	v_sub_f32_e32 v123, v123, v175
	v_sub_f32_e32 v124, v124, v175
	v_sub_f32_e32 v125, v125, v175
	v_sub_f32_e32 v126, v126, v175
	v_sub_f32_e32 v127, v127, v175
	v_exp_f32_e32 v120, v120
	v_exp_f32_e32 v121, v121
	v_exp_f32_e32 v122, v122
	v_exp_f32_e32 v123, v123
	v_exp_f32_e32 v124, v124
	v_exp_f32_e32 v125, v125
	v_exp_f32_e32 v126, v126
	v_exp_f32_e32 v127, v127
	v_add_f32_e32 v190, v190, v120
	v_add_f32_e32 v191, v191, v121
	v_add_f32_e32 v190, v190, v122
	v_add_f32_e32 v191, v191, v123
	v_add_f32_e32 v190, v190, v124
	v_add_f32_e32 v191, v191, v125
	v_add_f32_e32 v190, v190, v126
	v_add_f32_e32 v191, v191, v127
	v_cvt_pk_bf16_f32 v156, v120, v121
	v_cvt_pk_bf16_f32 v157, v122, v123
	v_cvt_pk_bf16_f32 v158, v124, v125
	v_cvt_pk_bf16_f32 v159, v126, v127
	v_add_f32_e32 v190, v190, v191
	v_fma_f32 v167, v167, v174, v190
	s_cbranch_vccz .Lattn_noresc_T31
	s_nop 7
	s_nop 7
	v_pk_mul_f32 v[0:1], v[0:1], v[174:175] op_sel_hi:[1,0]
	v_pk_mul_f32 v[2:3], v[2:3], v[174:175] op_sel_hi:[1,0]
	v_pk_mul_f32 v[4:5], v[4:5], v[174:175] op_sel_hi:[1,0]
	v_pk_mul_f32 v[6:7], v[6:7], v[174:175] op_sel_hi:[1,0]
	v_pk_mul_f32 v[8:9], v[8:9], v[174:175] op_sel_hi:[1,0]
	v_pk_mul_f32 v[10:11], v[10:11], v[174:175] op_sel_hi:[1,0]
	v_pk_mul_f32 v[12:13], v[12:13], v[174:175] op_sel_hi:[1,0]
	v_pk_mul_f32 v[14:15], v[14:15], v[174:175] op_sel_hi:[1,0]
	v_pk_mul_f32 v[16:17], v[16:17], v[174:175] op_sel_hi:[1,0]
	v_pk_mul_f32 v[18:19], v[18:19], v[174:175] op_sel_hi:[1,0]
	v_pk_mul_f32 v[20:21], v[20:21], v[174:175] op_sel_hi:[1,0]
	v_pk_mul_f32 v[22:23], v[22:23], v[174:175] op_sel_hi:[1,0]
	v_pk_mul_f32 v[24:25], v[24:25], v[174:175] op_sel_hi:[1,0]
	v_pk_mul_f32 v[26:27], v[26:27], v[174:175] op_sel_hi:[1,0]
	v_pk_mul_f32 v[28:29], v[28:29], v[174:175] op_sel_hi:[1,0]
	v_pk_mul_f32 v[30:31], v[30:31], v[174:175] op_sel_hi:[1,0]
	v_pk_mul_f32 v[32:33], v[32:33], v[174:175] op_sel_hi:[1,0]
	v_pk_mul_f32 v[34:35], v[34:35], v[174:175] op_sel_hi:[1,0]
	v_pk_mul_f32 v[36:37], v[36:37], v[174:175] op_sel_hi:[1,0]
	v_pk_mul_f32 v[38:39], v[38:39], v[174:175] op_sel_hi:[1,0]
	v_pk_mul_f32 v[40:41], v[40:41], v[174:175] op_sel_hi:[1,0]
	v_pk_mul_f32 v[42:43], v[42:43], v[174:175] op_sel_hi:[1,0]
	v_pk_mul_f32 v[44:45], v[44:45], v[174:175] op_sel_hi:[1,0]
	v_pk_mul_f32 v[46:47], v[46:47], v[174:175] op_sel_hi:[1,0]
	v_pk_mul_f32 v[48:49], v[48:49], v[174:175] op_sel_hi:[1,0]
	v_pk_mul_f32 v[50:51], v[50:51], v[174:175] op_sel_hi:[1,0]
	v_pk_mul_f32 v[52:53], v[52:53], v[174:175] op_sel_hi:[1,0]
	v_pk_mul_f32 v[54:55], v[54:55], v[174:175] op_sel_hi:[1,0]
	v_pk_mul_f32 v[56:57], v[56:57], v[174:175] op_sel_hi:[1,0]
	v_pk_mul_f32 v[58:59], v[58:59], v[174:175] op_sel_hi:[1,0]
	v_pk_mul_f32 v[60:61], v[60:61], v[174:175] op_sel_hi:[1,0]
	v_pk_mul_f32 v[62:63], v[62:63], v[174:175] op_sel_hi:[1,0]
	s_nop 1
